# attention softmax row-max via v_permlane16/32_swap instead of ds_bpermute round trips, stacked with next-unit index prefetch
# speedup vs baseline: 1.0030x; 1.0030x over previous
; #define LAS __attribute__((address_space(3)))
; __device__ __forceinline__ unsigned cvt_pk_bf16(float lo, float hi) { unsigned r; asm volatile("v_cvt_pk_bf16_f32 %0, %1, %2" : "=v"(r) : "v"(lo), "v"(hi)); return r; }
; __device__ __forceinline__ void attn_unit(LAS unsigned char* lds, bf16_t* proj, const float* biasG, const float* sink, int s, int qb, int kh, int hp, bf16_t* dummy = nullptr) {
;     ...
;                 mx = fmaxf(mx, __shfl_xor(mx, 16)); mx = fmaxf(mx, __shfl_xor(mx, 32));
;                 const float mnew = fmaxf(m2[qt], mx), alpha = __builtin_amdgcn_exp2f(m2[qt] - mnew); m2[qt] = mnew;
;                 float ps = 0.f; float pv[8];
; #pragma unroll
;                 for (int i = 0; i < 8; ++i) { pv[i] = __builtin_amdgcn_exp2f(sv[i] - mnew); ps += pv[i]; }
;                 lsum[qt] = lsum[qt] * alpha + ps;
; #pragma unroll
;                 for (int dt = 0; dt < 8; ++dt) o[dt][qt] = o[dt][qt] * alpha;
;                 u32x4 pw; pw.x = cvt_pk_bf16(pv[0], pv[1]); pw.y = cvt_pk_bf16(pv[2], pv[3]); pw.z = cvt_pk_bf16(pv[4], pv[5]); pw.w = cvt_pk_bf16(pv[6], pv[7]);
;                 pf[qt] = __builtin_bit_cast(bf16x8, pw);
;             }
; #pragma unroll
;             for (int dt = 0; dt < 8; ++dt) {
;                 const LAS unsigned char* vr = Vt + (dt * 16 + l16) * 288 + (si * 32 + kg * 4) * 2;
;                 const u32x2 lo = *(const LAS u32x2*)(vr), hi = *(const LAS u32x2*)(vr + 32);
;                 u32x4 vw; vw.x = lo.x; vw.y = lo.y; vw.z = hi.x; vw.w = hi.y;
;                 const bf16x8 vf = __builtin_bit_cast(bf16x8, vw);
;                 o[dt][0] = __builtin_amdgcn_mfma_f32_16x16x32_bf16(vf, pf[0], o[dt][0], 0, 0, 0);
;                 o[dt][1] = __builtin_amdgcn_mfma_f32_16x16x32_bf16(vf, pf[1], o[dt][1], 0, 0, 0);
.LBB0_661:
	s_or_b64 exec, exec, s[4:5]
	v_max3_f32 v2, v145, s89, v144
	v_max3_f32 v2, v2, v141, v140
	v_max3_f32 v139, v2, v143, v142
	v_add_f32_e32 v2, 0, v147
	v_add_f32_e32 v2, v228, v2
	v_add_f32_e32 v2, v229, v2
	v_sub_f32_e32 v138, v224, v1
	v_add_f32_e32 v2, v230, v2
	v_add_f32_e32 v2, v231, v2
	v_exp_f32_e32 v138, v138
	v_add_f32_e32 v2, v232, v2
	v_add_f32_e32 v2, v233, v2
	v_add_f32_e32 v2, v234, v2
	v_fmac_f32_e32 v2, v223, v138
	v_pk_mul_f32 v[98:99], v[98:99], v[138:139] op_sel_hi:[1,0]
	v_pk_mul_f32 v[96:97], v[96:97], v[138:139] op_sel_hi:[1,0]
	v_pk_mul_f32 v[106:107], v[106:107], v[138:139] op_sel_hi:[1,0]
	v_pk_mul_f32 v[104:105], v[104:105], v[138:139] op_sel_hi:[1,0]
	v_pk_mul_f32 v[110:111], v[110:111], v[138:139] op_sel_hi:[1,0]
	v_pk_mul_f32 v[108:109], v[108:109], v[138:139] op_sel_hi:[1,0]
	v_pk_mul_f32 v[114:115], v[114:115], v[138:139] op_sel_hi:[1,0]
	v_pk_mul_f32 v[112:113], v[112:113], v[138:139] op_sel_hi:[1,0]
	v_pk_mul_f32 v[118:119], v[118:119], v[138:139] op_sel_hi:[1,0]
	v_pk_mul_f32 v[116:117], v[116:117], v[138:139] op_sel_hi:[1,0]
	v_pk_mul_f32 v[122:123], v[122:123], v[138:139] op_sel_hi:[1,0]
	v_pk_mul_f32 v[120:121], v[120:121], v[138:139] op_sel_hi:[1,0]
	v_pk_mul_f32 v[126:127], v[126:127], v[138:139] op_sel_hi:[1,0]
	v_pk_mul_f32 v[124:125], v[124:125], v[138:139] op_sel_hi:[1,0]
	v_pk_mul_f32 v[130:131], v[130:131], v[138:139] op_sel_hi:[1,0]
	v_pk_mul_f32 v[128:129], v[128:129], v[138:139] op_sel_hi:[1,0]
	v_max3_f32 v138, v139, v137, v136
	v_mov_b32_e32 v253, v138
	v_mov_b32_e32 v139, v138
	s_nop 1
	v_permlane16_swap_b32_e32 v253, v139
	v_max_f32_e32 v139, v139, v253
	v_mov_b32_e32 v223, v2
	v_mov_b32_e32 v224, v1
	s_waitcnt lgkmcnt(0)
	v_max_f32_e32 v139, v139, v139
	v_max_f32_e32 v138, v138, v139
	v_mov_b32_e32 v253, v138
	v_mov_b32_e32 v3, v138
	s_nop 1
	v_permlane32_swap_b32_e32 v253, v3
	v_max_f32_e32 v3, v3, v253
	s_waitcnt lgkmcnt(0)
	v_max3_f32 v3, v222, v138, v3
	v_sub_f32_e32 v139, v145, v3
	v_exp_f32_e32 v139, v139
	v_sub_f32_e32 v144, v144, v3
	v_exp_f32_e32 v144, v144
	v_sub_f32_e32 v141, v141, v3
	v_exp_f32_e32 v141, v141
	v_sub_f32_e32 v140, v140, v3
	v_exp_f32_e32 v146, v140
	v_add_f32_e32 v145, 0, v139
	v_sub_f32_e32 v143, v143, v3
	v_add_f32_e32 v145, v144, v145
	v_exp_f32_e32 v143, v143
	v_sub_f32_e32 v142, v142, v3
	v_add_f32_e32 v145, v141, v145
	v_exp_f32_e32 v142, v142
	v_sub_f32_e32 v137, v137, v3
	v_add_f32_e32 v140, v146, v145
	v_exp_f32_e32 v145, v137
	v_sub_f32_e32 v136, v136, v3
	v_sub_f32_e32 v138, v222, v3
	v_exp_f32_e32 v147, v136
	v_add_f32_e32 v140, v143, v140
	v_exp_f32_e32 v136, v138
	v_add_f32_e32 v140, v142, v140
	v_add_f32_e32 v137, v145, v140
	v_add_f32_e32 v140, v147, v137
	v_fmac_f32_e32 v140, v221, v136
	v_pk_mul_f32 v[70:71], v[70:71], v[136:137] op_sel_hi:[1,0]
	v_pk_mul_f32 v[68:69], v[68:69], v[136:137] op_sel_hi:[1,0]
	v_pk_mul_f32 v[74:75], v[74:75], v[136:137] op_sel_hi:[1,0]
	v_pk_mul_f32 v[72:73], v[72:73], v[136:137] op_sel_hi:[1,0]
	v_pk_mul_f32 v[78:79], v[78:79], v[136:137] op_sel_hi:[1,0]
	v_pk_mul_f32 v[76:77], v[76:77], v[136:137] op_sel_hi:[1,0]
	v_pk_mul_f32 v[82:83], v[82:83], v[136:137] op_sel_hi:[1,0]
	v_pk_mul_f32 v[80:81], v[80:81], v[136:137] op_sel_hi:[1,0]
	v_pk_mul_f32 v[86:87], v[86:87], v[136:137] op_sel_hi:[1,0]
	v_pk_mul_f32 v[84:85], v[84:85], v[136:137] op_sel_hi:[1,0]
	v_pk_mul_f32 v[90:91], v[90:91], v[136:137] op_sel_hi:[1,0]
	v_pk_mul_f32 v[88:89], v[88:89], v[136:137] op_sel_hi:[1,0]
	v_pk_mul_f32 v[94:95], v[94:95], v[136:137] op_sel_hi:[1,0]
	v_pk_mul_f32 v[92:93], v[92:93], v[136:137] op_sel_hi:[1,0]
	v_pk_mul_f32 v[102:103], v[102:103], v[136:137] op_sel_hi:[1,0]
	v_pk_mul_f32 v[100:101], v[100:101], v[136:137] op_sel_hi:[1,0]
	v_cvt_pk_bf16_f32 v136, v139, v144
	v_cvt_pk_bf16_f32 v137, v141, v146
	v_add_u32_e32 v141, v197, v198
	v_cvt_pk_bf16_f32 v138, v143, v142
	v_add_u32_e32 v142, 0x8800, v141
	v_cvt_pk_bf16_f32 v139, v145, v147
	ds_read2_b64 v[236:239], v142 offset0:24 offset1:28
	v_mov_b32_e32 v221, v140
	v_add_u32_e32 v252, 0x9800, v141
	ds_read2_b64 v[240:243], v252 offset0:88 offset1:92
	v_add_u32_e32 v252, 0xa800, v141
	ds_read2_b64 v[244:247], v252 offset0:152 offset1:156
	v_add_u32_e32 v252, 0xb800, v141
	ds_read2_b64 v[248:251], v252 offset0:216 offset1:220
	s_waitcnt lgkmcnt(3)
	v_mfma_f32_16x16x32_bf16 v[96:99], v[236:239], v[132:135], v[96:99]
	v_mov_b32_e32 v222, v3
	v_mfma_f32_16x16x32_bf16 v[68:71], v[236:239], v[136:139], v[68:71]
	v_add_u32_e32 v252, 0xd000, v141
	ds_read2_b64 v[236:239], v252 offset0:24 offset1:28
	v_add_u32_e32 v141, 0xe000, v141
	s_waitcnt lgkmcnt(3)
	v_mfma_f32_16x16x32_bf16 v[104:107], v[240:243], v[132:135], v[104:107]
	v_mfma_f32_16x16x32_bf16 v[72:75], v[240:243], v[136:139], v[72:75]
	ds_read2_b64 v[240:243], v141 offset0:88 offset1:92
	s_waitcnt lgkmcnt(3)
	v_mfma_f32_16x16x32_bf16 v[108:111], v[244:247], v[132:135], v[108:111]
	v_mfma_f32_16x16x32_bf16 v[76:79], v[244:247], v[136:139], v[76:79]
	ds_read2_b64 v[244:247], v219 offset0:24 offset1:28
	s_waitcnt lgkmcnt(3)
	v_mfma_f32_16x16x32_bf16 v[112:115], v[248:251], v[132:135], v[112:115]
	v_mfma_f32_16x16x32_bf16 v[80:83], v[248:251], v[136:139], v[80:83]
	ds_read2_b64 v[248:251], v220 offset0:192 offset1:196
	s_waitcnt lgkmcnt(3)
	v_mfma_f32_16x16x32_bf16 v[116:119], v[236:239], v[132:135], v[116:119]
	v_mfma_f32_16x16x32_bf16 v[84:87], v[236:239], v[136:139], v[84:87]
	s_waitcnt lgkmcnt(2)
	v_mfma_f32_16x16x32_bf16 v[120:123], v[240:243], v[132:135], v[120:123]
	v_mfma_f32_16x16x32_bf16 v[88:91], v[240:243], v[136:139], v[88:91]
	s_waitcnt lgkmcnt(1)
	v_mfma_f32_16x16x32_bf16 v[124:127], v[244:247], v[132:135], v[124:127]
	v_mfma_f32_16x16x32_bf16 v[92:95], v[244:247], v[136:139], v[92:95]
	s_waitcnt lgkmcnt(0)
	v_mfma_f32_16x16x32_bf16 v[128:131], v[248:251], v[132:135], v[128:131]
	v_mfma_f32_16x16x32_bf16 v[100:103], v[248:251], v[136:139], v[100:103]

; #define LAS __attribute__((address_space(3)))
; __device__ __forceinline__ void attn_unit(LAS unsigned char* lds, bf16_t* proj, const float* biasG, const float* sink, int s, int qb, int kh, int hp, bf16_t* dummy = nullptr) {
;     ...
;         for (int si = 0; si < 4; ++si) {
;             const int st = kbi * 4 + si;
;             if (st < wq || st > wq + 8) continue;
;             f32x4 sa[2][2];
; #pragma unroll
;             for (int kt = 0; kt < 2; ++kt) { sa[kt][0] = (f32x4){0.f, 0.f, 0.f, 0.f}; sa[kt][1] = (f32x4){0.f, 0.f, 0.f, 0.f}; }
; #pragma unroll
;             for (int ks = 0; ks < 4; ++ks)
; #pragma unroll
;                 for (int kt = 0; kt < 2; ++kt) {
;                     const bf16x8 kf = *(const LAS bf16x8*)(Ks + (si * 32 + kt * 16 + l16) * 272 + ks * 64 + kg * 16);
;                     sa[kt][0] = __builtin_amdgcn_mfma_f32_16x16x32_bf16(kf, qf[0][ks], sa[kt][0], 0, 0, 0);
;                     sa[kt][1] = __builtin_amdgcn_mfma_f32_16x16x32_bf16(kf, qf[1][ks], sa[kt][1], 0, 0, 0);
;                 }
;             bf16x8 pf[2];
; #pragma unroll
;             for (int qt = 0; qt < 2; ++qt) {
;                 const int qp = wq * 32 + qt * 16 + l16;
;                 float sv[8]; float mx = -1e30f;
; #pragma unroll
;                 for (int kt = 0; kt < 2; ++kt)
; #pragma unroll
;                     for (int r = 0; r < 4; ++r) {
;                         const int kp = (kbi - 1) * 128 + si * 32 + kt * 16 + kg * 4 + r;
;                         const int rel = kp - qp; const bool valid = (rel >= -128) && (rel <= 128);
;                         const int idx = min(max(rel + 128, 0), 256);
;                         const float v = valid ? (sa[kt][qt][r] * SC + bL[hl * 260 + idx]) : -1e30f;
;                         sv[kt * 4 + r] = v; mx = fmaxf(mx, v);
;                     }
;                 mx = fmaxf(mx, __shfl_xor(mx, 16)); mx = fmaxf(mx, __shfl_xor(mx, 32));
.LBB0_665:
	s_add_i32 s19, s30, -3
	v_cmp_ge_u32_e32 vcc, s19, v192
	v_cmp_le_u32_e64 s[4:5], s19, v195
	s_and_b64 s[4:5], vcc, s[4:5]
	s_and_saveexec_b64 s[74:75], s[4:5]
	s_cbranch_execz .LBB0_699
	v_add_u32_e32 v251, 0x11700, v200
	v_add_u32_e32 v251, v251, v196
	v_add_u32_e32 v252, 0x11700, v201
	v_add_u32_e32 v252, v252, v196
	ds_read_b32 v235, v252 offset:256
	ds_read_b32 v236, v252 offset:260
	ds_read_b32 v237, v252 offset:264
	ds_read_b32 v238, v252 offset:268
	ds_read_b32 v239, v252 offset:320
	ds_read_b32 v240, v252 offset:324
	ds_read_b32 v241, v252 offset:328
	ds_read_b32 v242, v252 offset:332
	ds_read_b32 v243, v251 offset:192
	ds_read_b32 v244, v251 offset:196
	ds_read_b32 v245, v251 offset:200
	ds_read_b32 v246, v251 offset:204
	ds_read_b32 v247, v252 offset:256
	ds_read_b32 v248, v252 offset:260
	ds_read_b32 v249, v252 offset:264
	ds_read_b32 v250, v252 offset:268
	ds_read_b128 v[132:135], v213
	ds_read_b128 v[226:229], v213 offset:64
	ds_read_b128 v[140:143], v213 offset:4352
	v_add_u32_e32 v1, 0xffffff8d, v199
	v_cmp_gt_u32_e32 vcc, s53, v1
	v_add3_u32 v2, v201, v196, s31
	s_waitcnt lgkmcnt(0)
	v_mfma_f32_16x16x32_bf16 v[136:139], v[132:135], v[4:7], 0
	v_mfma_f32_16x16x32_bf16 v[132:135], v[132:135], v[20:23], 0
	v_mfma_f32_16x16x32_bf16 v[136:139], v[226:229], v[8:11], v[136:139]
	v_mfma_f32_16x16x32_bf16 v[132:135], v[226:229], v[24:27], v[132:135]
	ds_read_b128 v[226:229], v213 offset:4416
	v_mfma_f32_16x16x32_bf16 v[144:147], v[140:143], v[4:7], 0
	v_mfma_f32_16x16x32_bf16 v[140:143], v[140:143], v[20:23], 0
	s_waitcnt lgkmcnt(0)
	v_mfma_f32_16x16x32_bf16 v[144:147], v[226:229], v[8:11], v[144:147]
	v_mfma_f32_16x16x32_bf16 v[140:143], v[226:229], v[24:27], v[140:143]
	ds_read_b128 v[226:229], v213 offset:128
	s_waitcnt lgkmcnt(0)
	v_mfma_f32_16x16x32_bf16 v[136:139], v[226:229], v[12:15], v[136:139]
	v_mfma_f32_16x16x32_bf16 v[132:135], v[226:229], v[28:31], v[132:135]
	ds_read_b128 v[226:229], v213 offset:4480
	s_waitcnt lgkmcnt(0)
	v_mfma_f32_16x16x32_bf16 v[230:233], v[226:229], v[12:15], v[144:147]
	v_mfma_f32_16x16x32_bf16 v[226:229], v[226:229], v[28:31], v[140:143]
	s_nop 2
	ds_read_b128 v[140:143], v213 offset:192
	s_waitcnt lgkmcnt(0)
	v_mfma_f32_16x16x32_bf16 v[144:147], v[140:143], v[16:19], v[136:139]
	s_nop 2
	ds_read_b128 v[136:139], v213 offset:4544
	v_mfma_f32_16x16x32_bf16 v[140:143], v[140:143], v[32:35], v[132:135]
	s_waitcnt lgkmcnt(0)
	v_mfma_f32_16x16x32_bf16 v[132:135], v[136:139], v[16:19], v[230:233]
	v_mfma_f32_16x16x32_bf16 v[136:139], v[136:139], v[32:35], v[226:229]
	s_nop 2
	v_mov_b32_e32 v228, 0xf149f2ca
	v_mov_b32_e32 v229, 0xf149f2ca
	s_waitcnt lgkmcnt(0)
	v_fmac_f32_e32 v235, 0x3e0293ee, v144
	v_cndmask_b32_e32 v229, v229, v235, vcc
	v_add_u32_e32 v1, 0xffffff8e, v199
	v_cmp_gt_u32_e64 s[4:5], s53, v1
	v_add3_u32 v225, v201, v196, s40
	v_fmac_f32_e32 v236, 0x3e0293ee, v145
	v_cndmask_b32_e64 v228, v228, v236, s[4:5]
	v_add_u32_e32 v1, 0xffffff8f, v199
	v_cmp_gt_u32_e64 s[6:7], s53, v1
	v_mov_b32_e32 v145, 0xf149f2ca
	v_add3_u32 v226, v201, v196, s42
	v_mov_b32_e32 v230, 0xf149f2ca
	v_fmac_f32_e32 v237, 0x3e0293ee, v146
	v_cndmask_b32_e64 v230, v230, v237, s[6:7]
	v_add_u32_e32 v1, 0xffffff90, v199
	v_cmp_gt_u32_e64 s[8:9], s53, v1
	v_add3_u32 v227, v201, v196, s96
	v_fmac_f32_e32 v238, 0x3e0293ee, v147
	v_cndmask_b32_e64 v145, v145, v238, s[8:9]
	v_add_u32_e32 v1, 0xffffff9d, v199
	v_cmp_gt_u32_e64 s[10:11], s53, v1
	v_mov_b32_e32 v232, 0xf149f2ca
	v_mov_b32_e32 v231, 0xf149f2ca
	v_fmac_f32_e32 v239, 0x3e0293ee, v132
	v_cndmask_b32_e64 v231, v231, v239, s[10:11]
	v_add_u32_e32 v1, 0xffffff9e, v199
	v_cmp_gt_u32_e64 s[10:11], s53, v1
	v_fmac_f32_e32 v240, 0x3e0293ee, v133
	s_nop 0
	v_cndmask_b32_e64 v232, v232, v240, s[10:11]
	v_add_u32_e32 v1, 0xffffff9f, v199
	v_cmp_gt_u32_e64 s[10:11], s53, v1
	v_mov_b32_e32 v132, 0xf149f2ca
	v_mov_b32_e32 v133, 0xf149f2ca
	v_fmac_f32_e32 v241, 0x3e0293ee, v134
	v_cndmask_b32_e64 v133, v133, v241, s[10:11]
	v_add_u32_e32 v1, 0xffffffa0, v199
	v_cmp_gt_u32_e64 s[10:11], s53, v1
	v_fmac_f32_e32 v242, 0x3e0293ee, v135
	s_nop 0
	v_cndmask_b32_e64 v132, v132, v242, s[10:11]
	v_mov_b32_e32 v144, 0xf149f2ca
	v_and_b32_e32 v134, 64, v182
	v_max3_f32 v1, v229, v144, v228
	v_xor_b32_e32 v3, 16, v182
	v_add_u32_e32 v134, 64, v134
	v_max3_f32 v1, v1, v230, v145
	v_cmp_lt_i32_e64 s[10:11], v3, v134
	v_max3_f32 v1, v1, v231, v232
	v_max3_f32 v1, v1, v133, v132
	v_cndmask_b32_e64 v3, v182, v3, s[10:11]
	v_lshlrev_b32_e32 v146, 2, v3
	v_mov_b32_e32 v253, v1
	v_mov_b32_e32 v135, v1
	s_nop 1
	v_permlane16_swap_b32_e32 v253, v135
	v_max_f32_e32 v135, v135, v253
	v_xor_b32_e32 v3, 32, v182
	v_cmp_lt_i32_e64 s[10:11], v3, v134
	s_waitcnt lgkmcnt(0)
	v_max_f32_e32 v134, v135, v135
	v_cndmask_b32_e64 v3, v182, v3, s[10:11]
	v_lshlrev_b32_e32 v3, 2, v3
	v_max_f32_e32 v1, v1, v134
	v_mov_b32_e32 v253, v1
	v_mov_b32_e32 v134, v1
	s_nop 1
	v_permlane32_swap_b32_e32 v253, v134
	v_max_f32_e32 v134, v134, v253
	s_waitcnt lgkmcnt(0)
; #define LAS __attribute__((address_space(3)))
; __device__ __forceinline__ unsigned cvt_pk_bf16(float lo, float hi) { unsigned r; asm volatile("v_cvt_pk_bf16_f32 %0, %1, %2" : "=v"(r) : "v"(lo), "v"(hi)); return r; }
; __device__ __forceinline__ void attn_unit(LAS unsigned char* lds, bf16_t* proj, const float* biasG, const float* sink, int s, int qb, int kh, int hp, bf16_t* dummy = nullptr) {
;     ...
;             for (int qt = 0; qt < 2; ++qt) {
;                 const int qp = wq * 32 + qt * 16 + l16;
;                 float sv[8]; float mx = -1e30f;
; #pragma unroll
;                 for (int kt = 0; kt < 2; ++kt)
; #pragma unroll
;                     for (int r = 0; r < 4; ++r) {
;                         const int kp = (kbi - 1) * 128 + si * 32 + kt * 16 + kg * 4 + r;
;                         const int rel = kp - qp; const bool valid = (rel >= -128) && (rel <= 128);
;                         const int idx = min(max(rel + 128, 0), 256);
;                         const float v = valid ? (sa[kt][qt][r] * SC + bL[hl * 260 + idx]) : -1e30f;
;                         sv[kt * 4 + r] = v; mx = fmaxf(mx, v);
;                     }
;                 mx = fmaxf(mx, __shfl_xor(mx, 16)); mx = fmaxf(mx, __shfl_xor(mx, 32));
;                 const float mnew = fmaxf(m2[qt], mx), alpha = __builtin_amdgcn_exp2f(m2[qt] - mnew); m2[qt] = mnew;
;                 float ps = 0.f; float pv[8];
; #pragma unroll
;                 for (int i = 0; i < 8; ++i) { pv[i] = __builtin_amdgcn_exp2f(sv[i] - mnew); ps += pv[i]; }
;                 lsum[qt] = lsum[qt] * alpha + ps;
; #pragma unroll
;                 for (int dt = 0; dt < 8; ++dt) o[dt][qt] = o[dt][qt] * alpha;
;                 u32x4 pw; pw.x = cvt_pk_bf16(pv[0], pv[1]); pw.y = cvt_pk_bf16(pv[2], pv[3]); pw.z = cvt_pk_bf16(pv[4], pv[5]); pw.w = cvt_pk_bf16(pv[6], pv[7]);
;                 pf[qt] = __builtin_bit_cast(bf16x8, pw);
;             }
; #pragma unroll
;             for (int dt = 0; dt < 8; ++dt) {
;                 const LAS unsigned char* vr = Vt + (dt * 16 + l16) * 288 + (si * 32 + kg * 4) * 2;
;                 const u32x2 lo = *(const LAS u32x2*)(vr), hi = *(const LAS u32x2*)(vr + 32);
	v_max3_f32 v1, v224, v1, v134
	v_sub_f32_e32 v134, v229, v1
	v_exp_f32_e32 v147, v134
	v_sub_f32_e32 v134, v228, v1
	v_exp_f32_e32 v228, v134
	v_sub_f32_e32 v134, v230, v1
	v_exp_f32_e32 v229, v134
	v_sub_f32_e32 v134, v145, v1
	v_exp_f32_e32 v230, v134
	v_sub_f32_e32 v134, v231, v1
	v_exp_f32_e32 v231, v134
	v_sub_f32_e32 v134, v232, v1
	v_sub_f32_e32 v133, v133, v1
	v_sub_f32_e32 v132, v132, v1
	v_exp_f32_e32 v232, v134
	v_exp_f32_e32 v233, v133
	v_exp_f32_e32 v234, v132
	v_add_u32_e32 v145, 0xffffff7d, v199
	v_cmp_gt_u32_e64 s[10:11], s53, v145
	v_mov_b32_e32 v145, 0xf149f2ca
	v_cvt_pk_bf16_f32 v132, v147, v228
	v_cvt_pk_bf16_f32 v133, v229, v230
	v_cvt_pk_bf16_f32 v134, v231, v232
	v_cvt_pk_bf16_f32 v135, v233, v234
	v_fmac_f32_e32 v243, 0x3e0293ee, v140
	v_cndmask_b32_e64 v145, v145, v243, s[10:11]
	v_add_u32_e32 v140, 0xffffff7e, v199
	v_cmp_gt_u32_e64 s[10:11], s53, v140
	v_fmac_f32_e32 v244, 0x3e0293ee, v141
	s_nop 0
	v_cndmask_b32_e64 v144, v144, v244, s[10:11]
	v_add_u32_e32 v140, 0xffffff7f, v199
	v_cmp_gt_u32_e64 s[10:11], s53, v140
	v_mov_b32_e32 v140, 0xf149f2ca
	v_mov_b32_e32 v141, 0xf149f2ca
	v_fmac_f32_e32 v245, 0x3e0293ee, v142
	v_cndmask_b32_e64 v141, v141, v245, s[10:11]
	v_add_u32_e32 v142, 0xffffff80, v199
	v_cmp_gt_u32_e64 s[10:11], s53, v142
	v_fmac_f32_e32 v246, 0x3e0293ee, v143
	s_nop 0
	v_cndmask_b32_e64 v140, v140, v246, s[10:11]
	v_mov_b32_e32 v142, 0xf149f2ca
	v_mov_b32_e32 v143, 0xf149f2ca
	v_fmac_f32_e32 v247, 0x3e0293ee, v136
	v_cndmask_b32_e32 v143, v143, v247, vcc
	v_fmac_f32_e32 v248, 0x3e0293ee, v137
	v_cndmask_b32_e64 v142, v142, v248, s[4:5]
	v_mov_b32_e32 v136, 0xf149f2ca
	v_mov_b32_e32 v137, 0xf149f2ca
	v_fmac_f32_e32 v249, 0x3e0293ee, v138
	v_cndmask_b32_e64 v137, v137, v249, s[6:7]
	v_fmac_f32_e32 v250, 0x3e0293ee, v139
	v_cndmask_b32_e64 v136, v136, v250, s[8:9]
	v_max3_f32 v2, v145, s89, v144
	v_max3_f32 v2, v2, v141, v140
	v_max3_f32 v139, v2, v143, v142
	v_add_f32_e32 v2, 0, v147
	v_add_f32_e32 v2, v228, v2
	v_add_f32_e32 v2, v229, v2
	v_sub_f32_e32 v138, v224, v1
	v_add_f32_e32 v2, v230, v2
	v_add_f32_e32 v2, v231, v2
	v_exp_f32_e32 v138, v138
	v_add_f32_e32 v2, v232, v2
	v_add_f32_e32 v2, v233, v2
	v_add_f32_e32 v2, v234, v2
	v_fmac_f32_e32 v2, v223, v138
	v_pk_mul_f32 v[98:99], v[98:99], v[138:139] op_sel_hi:[1,0]
	v_pk_mul_f32 v[96:97], v[96:97], v[138:139] op_sel_hi:[1,0]
	v_pk_mul_f32 v[106:107], v[106:107], v[138:139] op_sel_hi:[1,0]
	v_pk_mul_f32 v[104:105], v[104:105], v[138:139] op_sel_hi:[1,0]
	v_pk_mul_f32 v[110:111], v[110:111], v[138:139] op_sel_hi:[1,0]
	v_pk_mul_f32 v[108:109], v[108:109], v[138:139] op_sel_hi:[1,0]
	v_pk_mul_f32 v[114:115], v[114:115], v[138:139] op_sel_hi:[1,0]
	v_pk_mul_f32 v[112:113], v[112:113], v[138:139] op_sel_hi:[1,0]
	v_pk_mul_f32 v[118:119], v[118:119], v[138:139] op_sel_hi:[1,0]
	v_pk_mul_f32 v[116:117], v[116:117], v[138:139] op_sel_hi:[1,0]
	v_pk_mul_f32 v[122:123], v[122:123], v[138:139] op_sel_hi:[1,0]
	v_pk_mul_f32 v[120:121], v[120:121], v[138:139] op_sel_hi:[1,0]
	v_pk_mul_f32 v[126:127], v[126:127], v[138:139] op_sel_hi:[1,0]
	v_pk_mul_f32 v[124:125], v[124:125], v[138:139] op_sel_hi:[1,0]
	v_pk_mul_f32 v[130:131], v[130:131], v[138:139] op_sel_hi:[1,0]
	v_pk_mul_f32 v[128:129], v[128:129], v[138:139] op_sel_hi:[1,0]
	v_max3_f32 v138, v139, v137, v136
	v_mov_b32_e32 v253, v138
	v_mov_b32_e32 v139, v138
	s_nop 1
	v_permlane16_swap_b32_e32 v253, v139
	v_max_f32_e32 v139, v139, v253
	v_mov_b32_e32 v223, v2
	v_mov_b32_e32 v224, v1
	s_waitcnt lgkmcnt(0)
	v_max_f32_e32 v139, v139, v139
	v_max_f32_e32 v138, v138, v139
	v_mov_b32_e32 v253, v138
	v_mov_b32_e32 v3, v138
	s_nop 1
	v_permlane32_swap_b32_e32 v253, v3
	v_max_f32_e32 v3, v3, v253
	s_waitcnt lgkmcnt(0)
	v_max3_f32 v3, v222, v138, v3
	v_sub_f32_e32 v139, v145, v3
	v_exp_f32_e32 v139, v139
	v_sub_f32_e32 v144, v144, v3
	v_exp_f32_e32 v144, v144
	v_sub_f32_e32 v141, v141, v3
	v_exp_f32_e32 v141, v141
	v_sub_f32_e32 v140, v140, v3
	v_exp_f32_e32 v146, v140
	v_add_f32_e32 v145, 0, v139
	v_sub_f32_e32 v143, v143, v3
	v_add_f32_e32 v145, v144, v145
	v_exp_f32_e32 v143, v143
	v_sub_f32_e32 v142, v142, v3
	v_add_f32_e32 v145, v141, v145
	v_exp_f32_e32 v142, v142
	v_sub_f32_e32 v137, v137, v3
	v_add_f32_e32 v140, v146, v145
	v_exp_f32_e32 v145, v137
	v_sub_f32_e32 v136, v136, v3
	v_sub_f32_e32 v138, v222, v3
	v_exp_f32_e32 v147, v136
	v_add_f32_e32 v140, v143, v140
	v_exp_f32_e32 v136, v138
	v_add_f32_e32 v140, v142, v140
	v_add_f32_e32 v137, v145, v140
	v_add_f32_e32 v140, v147, v137
	v_fmac_f32_e32 v140, v221, v136
	v_pk_mul_f32 v[70:71], v[70:71], v[136:137] op_sel_hi:[1,0]
	v_pk_mul_f32 v[68:69], v[68:69], v[136:137] op_sel_hi:[1,0]
	v_pk_mul_f32 v[74:75], v[74:75], v[136:137] op_sel_hi:[1,0]
	v_pk_mul_f32 v[72:73], v[72:73], v[136:137] op_sel_hi:[1,0]
	v_pk_mul_f32 v[78:79], v[78:79], v[136:137] op_sel_hi:[1,0]
	v_pk_mul_f32 v[76:77], v[76:77], v[136:137] op_sel_hi:[1,0]
	v_pk_mul_f32 v[82:83], v[82:83], v[136:137] op_sel_hi:[1,0]
	v_pk_mul_f32 v[80:81], v[80:81], v[136:137] op_sel_hi:[1,0]
	v_pk_mul_f32 v[86:87], v[86:87], v[136:137] op_sel_hi:[1,0]
	v_pk_mul_f32 v[84:85], v[84:85], v[136:137] op_sel_hi:[1,0]
	v_pk_mul_f32 v[90:91], v[90:91], v[136:137] op_sel_hi:[1,0]
	v_pk_mul_f32 v[88:89], v[88:89], v[136:137] op_sel_hi:[1,0]
	v_pk_mul_f32 v[94:95], v[94:95], v[136:137] op_sel_hi:[1,0]
	v_pk_mul_f32 v[92:93], v[92:93], v[136:137] op_sel_hi:[1,0]
	v_pk_mul_f32 v[102:103], v[102:103], v[136:137] op_sel_hi:[1,0]
	v_pk_mul_f32 v[100:101], v[100:101], v[136:137] op_sel_hi:[1,0]
	v_cvt_pk_bf16_f32 v136, v139, v144
	v_cvt_pk_bf16_f32 v137, v141, v146
	v_add_u32_e32 v141, v197, v198
	v_cvt_pk_bf16_f32 v138, v143, v142
	v_add_u32_e32 v142, 0x8800, v141
	v_cvt_pk_bf16_f32 v139, v145, v147
	ds_read2_b64 v[236:239], v142 offset1:4
	v_mov_b32_e32 v221, v140
	v_add_u32_e32 v252, 0x9800, v141
	ds_read2_b64 v[240:243], v252 offset0:64 offset1:68
	v_add_u32_e32 v252, 0xa800, v141
	ds_read2_b64 v[244:247], v252 offset0:128 offset1:132
	v_add_u32_e32 v252, 0xb800, v141
	ds_read2_b64 v[248:251], v252 offset0:192 offset1:196
	s_waitcnt lgkmcnt(3)
; __device__ __forceinline__ void attn_unit(LAS unsigned char* lds, bf16_t* proj, const float* biasG, const float* sink, int s, int qb, int kh, int hp, bf16_t* dummy = nullptr) {
;     ...
;         for (int si = 0; si < 4; ++si) {
;             const int st = kbi * 4 + si;
;             if (st < wq || st > wq + 8) continue;
;             f32x4 sa[2][2];
; #pragma unroll
;             for (int kt = 0; kt < 2; ++kt) { sa[kt][0] = (f32x4){0.f, 0.f, 0.f, 0.f}; sa[kt][1] = (f32x4){0.f, 0.f, 0.f, 0.f}; }
; #pragma unroll
;             for (int ks = 0; ks < 4; ++ks)
; #pragma unroll
;                 for (int kt = 0; kt < 2; ++kt) {
;                     const bf16x8 kf = *(const LAS bf16x8*)(Ks + (si * 32 + kt * 16 + l16) * 272 + ks * 64 + kg * 16);
;                     sa[kt][0] = __builtin_amdgcn_mfma_f32_16x16x32_bf16(kf, qf[0][ks], sa[kt][0], 0, 0, 0);
;                     sa[kt][1] = __builtin_amdgcn_mfma_f32_16x16x32_bf16(kf, qf[1][ks], sa[kt][1], 0, 0, 0);
;                 }
;             bf16x8 pf[2];
; #pragma unroll
;             for (int qt = 0; qt < 2; ++qt) {
;                 const int qp = wq * 32 + qt * 16 + l16;
;                 float sv[8]; float mx = -1e30f;
; #pragma unroll
;                 for (int kt = 0; kt < 2; ++kt)
; #pragma unroll
;                     for (int r = 0; r < 4; ++r) {
;                         const int kp = (kbi - 1) * 128 + si * 32 + kt * 16 + kg * 4 + r;
;                         const int rel = kp - qp; const bool valid = (rel >= -128) && (rel <= 128);
;                         const int idx = min(max(rel + 128, 0), 256);
;                         const float v = valid ? (sa[kt][qt][r] * SC + bL[hl * 260 + idx]) : -1e30f;
;                         sv[kt * 4 + r] = v; mx = fmaxf(mx, v);
;                     }
;     ...
;             for (int dt = 0; dt < 8; ++dt) {
;                 const LAS unsigned char* vr = Vt + (dt * 16 + l16) * 288 + (si * 32 + kg * 4) * 2;
;                 const u32x2 lo = *(const LAS u32x2*)(vr), hi = *(const LAS u32x2*)(vr + 32);
;                 u32x4 vw; vw.x = lo.x; vw.y = lo.y; vw.z = hi.x; vw.w = hi.y;
;                 const bf16x8 vf = __builtin_bit_cast(bf16x8, vw);
;                 o[dt][0] = __builtin_amdgcn_mfma_f32_16x16x32_bf16(vf, pf[0], o[dt][0], 0, 0, 0);
;                 o[dt][1] = __builtin_amdgcn_mfma_f32_16x16x32_bf16(vf, pf[1], o[dt][1], 0, 0, 0);
	v_mfma_f32_16x16x32_bf16 v[96:99], v[236:239], v[132:135], v[96:99]
	v_mov_b32_e32 v222, v3
	v_mfma_f32_16x16x32_bf16 v[68:71], v[236:239], v[136:139], v[68:71]
	v_add_u32_e32 v252, 0xd000, v141
	ds_read2_b64 v[236:239], v252 offset1:4
	s_waitcnt lgkmcnt(3)
	v_mfma_f32_16x16x32_bf16 v[104:107], v[240:243], v[132:135], v[104:107]
	v_mfma_f32_16x16x32_bf16 v[72:75], v[240:243], v[136:139], v[72:75]
	v_add_u32_e32 v252, 0xe000, v141
	ds_read2_b64 v[240:243], v252 offset0:64 offset1:68
	v_add_u32_e32 v141, 0xf000, v141
	s_waitcnt lgkmcnt(3)
	v_mfma_f32_16x16x32_bf16 v[108:111], v[244:247], v[132:135], v[108:111]
	v_mfma_f32_16x16x32_bf16 v[76:79], v[244:247], v[136:139], v[76:79]
	ds_read2_b64 v[244:247], v141 offset0:128 offset1:132
	s_waitcnt lgkmcnt(3)
	v_mfma_f32_16x16x32_bf16 v[112:115], v[248:251], v[132:135], v[112:115]
	v_mfma_f32_16x16x32_bf16 v[80:83], v[248:251], v[136:139], v[80:83]
	ds_read2_b64 v[248:251], v214 offset0:192 offset1:196
	s_waitcnt lgkmcnt(3)
	v_mfma_f32_16x16x32_bf16 v[116:119], v[236:239], v[132:135], v[116:119]
	v_mfma_f32_16x16x32_bf16 v[84:87], v[236:239], v[136:139], v[84:87]
	s_waitcnt lgkmcnt(2)
	v_mfma_f32_16x16x32_bf16 v[120:123], v[240:243], v[132:135], v[120:123]
	v_mfma_f32_16x16x32_bf16 v[88:91], v[240:243], v[136:139], v[88:91]
	s_waitcnt lgkmcnt(1)
	v_mfma_f32_16x16x32_bf16 v[124:127], v[244:247], v[132:135], v[124:127]
	v_mfma_f32_16x16x32_bf16 v[92:95], v[244:247], v[136:139], v[92:95]
	s_waitcnt lgkmcnt(0)
	v_mfma_f32_16x16x32_bf16 v[128:131], v[248:251], v[132:135], v[128:131]
	v_mfma_f32_16x16x32_bf16 v[100:103], v[248:251], v[136:139], v[100:103]
.LBB0_699:
	s_or_b64 exec, exec, s[74:75]
	s_add_i32 s4, s30, -2
	v_cmp_ge_u32_e32 vcc, s4, v192
	v_cmp_lt_u32_e64 s[4:5], s19, v195
	s_and_b64 s[4:5], vcc, s[4:5]
	s_and_saveexec_b64 s[74:75], s[4:5]
	s_cbranch_execz .LBB0_733
	v_add_u32_e32 v251, 0x11700, v201
	v_add_u32_e32 v251, v251, v196
	ds_read_b32 v235, v251 offset:384
	ds_read_b32 v236, v251 offset:388
	ds_read_b32 v237, v251 offset:392
	ds_read_b32 v238, v251 offset:396
	ds_read_b32 v239, v251 offset:448
	ds_read_b32 v240, v251 offset:452
	ds_read_b32 v241, v251 offset:456
	ds_read_b32 v242, v251 offset:460
	ds_read_b32 v243, v251 offset:320
	ds_read_b32 v244, v251 offset:324
	ds_read_b32 v245, v251 offset:328
	ds_read_b32 v246, v251 offset:332
	ds_read_b32 v247, v251 offset:384
	ds_read_b32 v248, v251 offset:388
	ds_read_b32 v249, v251 offset:392
	ds_read_b32 v250, v251 offset:396
	ds_read_b128 v[132:135], v210
	ds_read_b128 v[226:229], v210 offset:64
	ds_read_b128 v[140:143], v213 offset:13056
	v_add_u32_e32 v1, 0xffffffad, v199
	v_cmp_gt_u32_e32 vcc, s53, v1
	v_add3_u32 v2, v201, v196, s88
	s_waitcnt lgkmcnt(0)
	v_mfma_f32_16x16x32_bf16 v[136:139], v[132:135], v[4:7], 0
	v_mfma_f32_16x16x32_bf16 v[132:135], v[132:135], v[20:23], 0
	v_mfma_f32_16x16x32_bf16 v[136:139], v[226:229], v[8:11], v[136:139]
	v_mfma_f32_16x16x32_bf16 v[132:135], v[226:229], v[24:27], v[132:135]
	ds_read_b128 v[226:229], v213 offset:13120
	v_mfma_f32_16x16x32_bf16 v[144:147], v[140:143], v[4:7], 0
	v_mfma_f32_16x16x32_bf16 v[140:143], v[140:143], v[20:23], 0
	s_waitcnt lgkmcnt(0)
	v_mfma_f32_16x16x32_bf16 v[144:147], v[226:229], v[8:11], v[144:147]
	v_mfma_f32_16x16x32_bf16 v[140:143], v[226:229], v[24:27], v[140:143]
	ds_read_b128 v[226:229], v210 offset:128
	s_waitcnt lgkmcnt(0)
	v_mfma_f32_16x16x32_bf16 v[136:139], v[226:229], v[12:15], v[136:139]
	v_mfma_f32_16x16x32_bf16 v[132:135], v[226:229], v[28:31], v[132:135]
	ds_read_b128 v[226:229], v213 offset:13184
	s_waitcnt lgkmcnt(0)
	v_mfma_f32_16x16x32_bf16 v[230:233], v[226:229], v[12:15], v[144:147]
	v_mfma_f32_16x16x32_bf16 v[226:229], v[226:229], v[28:31], v[140:143]
	s_nop 2
	ds_read_b128 v[140:143], v210 offset:192
	s_waitcnt lgkmcnt(0)
	v_mfma_f32_16x16x32_bf16 v[144:147], v[140:143], v[16:19], v[136:139]
	s_nop 2
	ds_read_b128 v[136:139], v213 offset:13248
	v_mfma_f32_16x16x32_bf16 v[140:143], v[140:143], v[32:35], v[132:135]
	s_waitcnt lgkmcnt(0)
	v_mfma_f32_16x16x32_bf16 v[132:135], v[136:139], v[16:19], v[230:233]
	v_mfma_f32_16x16x32_bf16 v[136:139], v[136:139], v[32:35], v[226:229]
	s_nop 2
	v_mov_b32_e32 v228, 0xf149f2ca
	v_mov_b32_e32 v229, 0xf149f2ca
	s_waitcnt lgkmcnt(0)
	v_fmac_f32_e32 v235, 0x3e0293ee, v144
	v_cndmask_b32_e32 v229, v229, v235, vcc
	v_add_u32_e32 v1, 0xffffffae, v199
	v_cmp_gt_u32_e64 s[4:5], s53, v1
	v_add3_u32 v225, v201, v196, s55
	v_fmac_f32_e32 v236, 0x3e0293ee, v145
	v_cndmask_b32_e64 v228, v228, v236, s[4:5]
	v_add_u32_e32 v1, 0xffffffaf, v199
	v_cmp_gt_u32_e64 s[6:7], s53, v1
	v_mov_b32_e32 v145, 0xf149f2ca
	v_add3_u32 v226, v201, v196, s59
	v_mov_b32_e32 v230, 0xf149f2ca
	v_fmac_f32_e32 v237, 0x3e0293ee, v146
	v_cndmask_b32_e64 v230, v230, v237, s[6:7]
	v_add_u32_e32 v1, 0xffffffb0, v199
	v_cmp_gt_u32_e64 s[8:9], s53, v1
	v_add3_u32 v227, v201, v196, s43
	v_fmac_f32_e32 v238, 0x3e0293ee, v147
	v_cndmask_b32_e64 v145, v145, v238, s[8:9]
	v_add_u32_e32 v1, 0xffffffbd, v199
	v_cmp_gt_u32_e64 s[10:11], s53, v1
	v_mov_b32_e32 v232, 0xf149f2ca
	v_mov_b32_e32 v231, 0xf149f2ca
	v_fmac_f32_e32 v239, 0x3e0293ee, v132
	v_cndmask_b32_e64 v231, v231, v239, s[10:11]
	v_add_u32_e32 v1, 0xffffffbe, v199
	v_cmp_gt_u32_e64 s[10:11], s53, v1
	v_fmac_f32_e32 v240, 0x3e0293ee, v133
	s_nop 0
	v_cndmask_b32_e64 v232, v232, v240, s[10:11]
	v_add_u32_e32 v1, 0xffffffbf, v199
	v_cmp_gt_u32_e64 s[10:11], s53, v1
	v_mov_b32_e32 v132, 0xf149f2ca
	v_mov_b32_e32 v133, 0xf149f2ca
	v_fmac_f32_e32 v241, 0x3e0293ee, v134
	v_cndmask_b32_e64 v133, v133, v241, s[10:11]
	v_subrev_u32_e32 v1, 64, v199
	v_cmp_gt_u32_e64 s[10:11], s53, v1
	v_fmac_f32_e32 v242, 0x3e0293ee, v135
	s_nop 0
	v_cndmask_b32_e64 v132, v132, v242, s[10:11]
	v_mov_b32_e32 v144, 0xf149f2ca
	v_and_b32_e32 v134, 64, v182
	v_max3_f32 v1, v229, v144, v228
	v_xor_b32_e32 v3, 16, v182
	v_add_u32_e32 v134, 64, v134
	v_max3_f32 v1, v1, v230, v145
	v_cmp_lt_i32_e64 s[10:11], v3, v134
	v_max3_f32 v1, v1, v231, v232
	v_max3_f32 v1, v1, v133, v132
	v_cndmask_b32_e64 v3, v182, v3, s[10:11]
	v_lshlrev_b32_e32 v146, 2, v3
	v_mov_b32_e32 v253, v1
	v_mov_b32_e32 v135, v1
	s_nop 1
	v_permlane16_swap_b32_e32 v253, v135
	v_max_f32_e32 v135, v135, v253
	v_xor_b32_e32 v3, 32, v182
	v_cmp_lt_i32_e64 s[10:11], v3, v134
	s_waitcnt lgkmcnt(0)
; #define LAS __attribute__((address_space(3)))
; __device__ __forceinline__ unsigned cvt_pk_bf16(float lo, float hi) { unsigned r; asm volatile("v_cvt_pk_bf16_f32 %0, %1, %2" : "=v"(r) : "v"(lo), "v"(hi)); return r; }
; __device__ __forceinline__ void attn_unit(LAS unsigned char* lds, bf16_t* proj, const float* biasG, const float* sink, int s, int qb, int kh, int hp, bf16_t* dummy = nullptr) {
;     ...
;                 mx = fmaxf(mx, __shfl_xor(mx, 16)); mx = fmaxf(mx, __shfl_xor(mx, 32));
;                 const float mnew = fmaxf(m2[qt], mx), alpha = __builtin_amdgcn_exp2f(m2[qt] - mnew); m2[qt] = mnew;
;                 float ps = 0.f; float pv[8];
; #pragma unroll
;                 for (int i = 0; i < 8; ++i) { pv[i] = __builtin_amdgcn_exp2f(sv[i] - mnew); ps += pv[i]; }
;                 lsum[qt] = lsum[qt] * alpha + ps;
; #pragma unroll
;                 for (int dt = 0; dt < 8; ++dt) o[dt][qt] = o[dt][qt] * alpha;
;                 u32x4 pw; pw.x = cvt_pk_bf16(pv[0], pv[1]); pw.y = cvt_pk_bf16(pv[2], pv[3]); pw.z = cvt_pk_bf16(pv[4], pv[5]); pw.w = cvt_pk_bf16(pv[6], pv[7]);
;                 pf[qt] = __builtin_bit_cast(bf16x8, pw);
;             }
; #pragma unroll
;             for (int dt = 0; dt < 8; ++dt) {
;                 const LAS unsigned char* vr = Vt + (dt * 16 + l16) * 288 + (si * 32 + kg * 4) * 2;
;                 const u32x2 lo = *(const LAS u32x2*)(vr), hi = *(const LAS u32x2*)(vr + 32);
	v_max_f32_e32 v134, v135, v135
	v_cndmask_b32_e64 v3, v182, v3, s[10:11]
	v_lshlrev_b32_e32 v3, 2, v3
	v_max_f32_e32 v1, v1, v134
	v_mov_b32_e32 v253, v1
	v_mov_b32_e32 v134, v1
	s_nop 1
	v_permlane32_swap_b32_e32 v253, v134
	v_max_f32_e32 v134, v134, v253
	s_waitcnt lgkmcnt(0)
	v_max3_f32 v1, v224, v1, v134
	v_sub_f32_e32 v134, v229, v1
	v_exp_f32_e32 v147, v134
	v_sub_f32_e32 v134, v228, v1
	v_exp_f32_e32 v228, v134
	v_sub_f32_e32 v134, v230, v1
	v_exp_f32_e32 v229, v134
	v_sub_f32_e32 v134, v145, v1
	v_exp_f32_e32 v230, v134
	v_sub_f32_e32 v134, v231, v1
	v_exp_f32_e32 v231, v134
	v_sub_f32_e32 v134, v232, v1
	v_sub_f32_e32 v133, v133, v1
	v_sub_f32_e32 v132, v132, v1
	v_exp_f32_e32 v232, v134
	v_exp_f32_e32 v233, v133
	v_exp_f32_e32 v234, v132
	v_add_u32_e32 v145, 0xffffff9d, v199
	v_cmp_gt_u32_e64 s[10:11], s53, v145
	v_mov_b32_e32 v145, 0xf149f2ca
	v_cvt_pk_bf16_f32 v132, v147, v228
	v_cvt_pk_bf16_f32 v133, v229, v230
	v_cvt_pk_bf16_f32 v134, v231, v232
	v_cvt_pk_bf16_f32 v135, v233, v234
	v_fmac_f32_e32 v243, 0x3e0293ee, v140
	v_cndmask_b32_e64 v145, v145, v243, s[10:11]
	v_add_u32_e32 v140, 0xffffff9e, v199
	v_cmp_gt_u32_e64 s[10:11], s53, v140
	v_fmac_f32_e32 v244, 0x3e0293ee, v141
	s_nop 0
	v_cndmask_b32_e64 v144, v144, v244, s[10:11]
	v_add_u32_e32 v140, 0xffffff9f, v199
	v_cmp_gt_u32_e64 s[10:11], s53, v140
	v_mov_b32_e32 v140, 0xf149f2ca
	v_mov_b32_e32 v141, 0xf149f2ca
	v_fmac_f32_e32 v245, 0x3e0293ee, v142
	v_cndmask_b32_e64 v141, v141, v245, s[10:11]
	v_add_u32_e32 v142, 0xffffffa0, v199
	v_cmp_gt_u32_e64 s[10:11], s53, v142
	v_fmac_f32_e32 v246, 0x3e0293ee, v143
	s_nop 0
	v_cndmask_b32_e64 v140, v140, v246, s[10:11]
	v_mov_b32_e32 v142, 0xf149f2ca
	v_mov_b32_e32 v143, 0xf149f2ca
	v_fmac_f32_e32 v247, 0x3e0293ee, v136
	v_cndmask_b32_e32 v143, v143, v247, vcc
	v_fmac_f32_e32 v248, 0x3e0293ee, v137
	v_cndmask_b32_e64 v142, v142, v248, s[4:5]
	v_mov_b32_e32 v136, 0xf149f2ca
	v_mov_b32_e32 v137, 0xf149f2ca
	v_fmac_f32_e32 v249, 0x3e0293ee, v138
	v_cndmask_b32_e64 v137, v137, v249, s[6:7]
	v_fmac_f32_e32 v250, 0x3e0293ee, v139
	v_cndmask_b32_e64 v136, v136, v250, s[8:9]
	v_max3_f32 v2, v145, s89, v144
	v_max3_f32 v2, v2, v141, v140
	v_max3_f32 v139, v2, v143, v142
	v_add_f32_e32 v2, 0, v147
	v_add_f32_e32 v2, v228, v2
	v_add_f32_e32 v2, v229, v2
	v_sub_f32_e32 v138, v224, v1
	v_add_f32_e32 v2, v230, v2
	v_add_f32_e32 v2, v231, v2
	v_exp_f32_e32 v138, v138
	v_add_f32_e32 v2, v232, v2
	v_add_f32_e32 v2, v233, v2
	v_add_f32_e32 v2, v234, v2
	v_fmac_f32_e32 v2, v223, v138
	v_pk_mul_f32 v[98:99], v[98:99], v[138:139] op_sel_hi:[1,0]
	v_pk_mul_f32 v[96:97], v[96:97], v[138:139] op_sel_hi:[1,0]
	v_pk_mul_f32 v[106:107], v[106:107], v[138:139] op_sel_hi:[1,0]
	v_pk_mul_f32 v[104:105], v[104:105], v[138:139] op_sel_hi:[1,0]
	v_pk_mul_f32 v[110:111], v[110:111], v[138:139] op_sel_hi:[1,0]
	v_pk_mul_f32 v[108:109], v[108:109], v[138:139] op_sel_hi:[1,0]
	v_pk_mul_f32 v[114:115], v[114:115], v[138:139] op_sel_hi:[1,0]
	v_pk_mul_f32 v[112:113], v[112:113], v[138:139] op_sel_hi:[1,0]
	v_pk_mul_f32 v[118:119], v[118:119], v[138:139] op_sel_hi:[1,0]
	v_pk_mul_f32 v[116:117], v[116:117], v[138:139] op_sel_hi:[1,0]
	v_pk_mul_f32 v[122:123], v[122:123], v[138:139] op_sel_hi:[1,0]
	v_pk_mul_f32 v[120:121], v[120:121], v[138:139] op_sel_hi:[1,0]
	v_pk_mul_f32 v[126:127], v[126:127], v[138:139] op_sel_hi:[1,0]
	v_pk_mul_f32 v[124:125], v[124:125], v[138:139] op_sel_hi:[1,0]
	v_pk_mul_f32 v[130:131], v[130:131], v[138:139] op_sel_hi:[1,0]
	v_pk_mul_f32 v[128:129], v[128:129], v[138:139] op_sel_hi:[1,0]
	v_max3_f32 v138, v139, v137, v136
	v_mov_b32_e32 v253, v138
	v_mov_b32_e32 v139, v138
	s_nop 1
	v_permlane16_swap_b32_e32 v253, v139
	v_max_f32_e32 v139, v139, v253
	v_mov_b32_e32 v223, v2
	v_mov_b32_e32 v224, v1
	s_waitcnt lgkmcnt(0)
	v_max_f32_e32 v139, v139, v139
	v_max_f32_e32 v138, v138, v139
	v_mov_b32_e32 v253, v138
	v_mov_b32_e32 v3, v138
	s_nop 1
	v_permlane32_swap_b32_e32 v253, v3
	v_max_f32_e32 v3, v3, v253
	s_waitcnt lgkmcnt(0)
	v_max3_f32 v3, v222, v138, v3
	v_sub_f32_e32 v139, v145, v3
	v_exp_f32_e32 v139, v139
	v_sub_f32_e32 v144, v144, v3
	v_exp_f32_e32 v144, v144
	v_sub_f32_e32 v141, v141, v3
	v_exp_f32_e32 v141, v141
	v_sub_f32_e32 v140, v140, v3
	v_exp_f32_e32 v146, v140
	v_add_f32_e32 v145, 0, v139
	v_sub_f32_e32 v143, v143, v3
	v_add_f32_e32 v145, v144, v145
	v_exp_f32_e32 v143, v143
	v_sub_f32_e32 v142, v142, v3
	v_add_f32_e32 v145, v141, v145
	v_exp_f32_e32 v142, v142
	v_sub_f32_e32 v137, v137, v3
	v_add_f32_e32 v140, v146, v145
	v_exp_f32_e32 v145, v137
	v_sub_f32_e32 v136, v136, v3
	v_sub_f32_e32 v138, v222, v3
	v_exp_f32_e32 v147, v136
	v_add_f32_e32 v140, v143, v140
	v_exp_f32_e32 v136, v138
	v_add_f32_e32 v140, v142, v140
	v_add_f32_e32 v137, v145, v140
	v_add_f32_e32 v140, v147, v137
	v_fmac_f32_e32 v140, v221, v136
	v_pk_mul_f32 v[70:71], v[70:71], v[136:137] op_sel_hi:[1,0]
	v_pk_mul_f32 v[68:69], v[68:69], v[136:137] op_sel_hi:[1,0]
	v_pk_mul_f32 v[74:75], v[74:75], v[136:137] op_sel_hi:[1,0]
	v_pk_mul_f32 v[72:73], v[72:73], v[136:137] op_sel_hi:[1,0]
	v_pk_mul_f32 v[78:79], v[78:79], v[136:137] op_sel_hi:[1,0]
	v_pk_mul_f32 v[76:77], v[76:77], v[136:137] op_sel_hi:[1,0]
	v_pk_mul_f32 v[82:83], v[82:83], v[136:137] op_sel_hi:[1,0]
	v_pk_mul_f32 v[80:81], v[80:81], v[136:137] op_sel_hi:[1,0]
	v_pk_mul_f32 v[86:87], v[86:87], v[136:137] op_sel_hi:[1,0]
	v_pk_mul_f32 v[84:85], v[84:85], v[136:137] op_sel_hi:[1,0]
	v_pk_mul_f32 v[90:91], v[90:91], v[136:137] op_sel_hi:[1,0]
	v_pk_mul_f32 v[88:89], v[88:89], v[136:137] op_sel_hi:[1,0]
	v_pk_mul_f32 v[94:95], v[94:95], v[136:137] op_sel_hi:[1,0]
	v_pk_mul_f32 v[92:93], v[92:93], v[136:137] op_sel_hi:[1,0]
	v_pk_mul_f32 v[102:103], v[102:103], v[136:137] op_sel_hi:[1,0]
	v_pk_mul_f32 v[100:101], v[100:101], v[136:137] op_sel_hi:[1,0]
	v_cvt_pk_bf16_f32 v136, v139, v144
	v_cvt_pk_bf16_f32 v137, v141, v146
	v_add_u32_e32 v141, v197, v198
	v_cvt_pk_bf16_f32 v138, v143, v142
	v_add_u32_e32 v142, 0x8800, v141
	v_cvt_pk_bf16_f32 v139, v145, v147
	ds_read2_b64 v[236:239], v142 offset0:8 offset1:12
	v_mov_b32_e32 v221, v140
	v_add_u32_e32 v252, 0x9800, v141
	ds_read2_b64 v[240:243], v252 offset0:72 offset1:76
	ds_read2_b64 v[244:247], v215 offset0:8 offset1:12
	v_add_u32_e32 v252, 0xb800, v141
	ds_read2_b64 v[248:251], v252 offset0:200 offset1:204
	s_waitcnt lgkmcnt(3)
; __device__ __forceinline__ void attn_unit(LAS unsigned char* lds, bf16_t* proj, const float* biasG, const float* sink, int s, int qb, int kh, int hp, bf16_t* dummy = nullptr) {
;     ...
;         for (int si = 0; si < 4; ++si) {
;             const int st = kbi * 4 + si;
;             if (st < wq || st > wq + 8) continue;
;             f32x4 sa[2][2];
; #pragma unroll
;             for (int kt = 0; kt < 2; ++kt) { sa[kt][0] = (f32x4){0.f, 0.f, 0.f, 0.f}; sa[kt][1] = (f32x4){0.f, 0.f, 0.f, 0.f}; }
; #pragma unroll
;             for (int ks = 0; ks < 4; ++ks)
; #pragma unroll
;                 for (int kt = 0; kt < 2; ++kt) {
;                     const bf16x8 kf = *(const LAS bf16x8*)(Ks + (si * 32 + kt * 16 + l16) * 272 + ks * 64 + kg * 16);
;                     sa[kt][0] = __builtin_amdgcn_mfma_f32_16x16x32_bf16(kf, qf[0][ks], sa[kt][0], 0, 0, 0);
;                     sa[kt][1] = __builtin_amdgcn_mfma_f32_16x16x32_bf16(kf, qf[1][ks], sa[kt][1], 0, 0, 0);
;                 }
;             bf16x8 pf[2];
; #pragma unroll
;             for (int qt = 0; qt < 2; ++qt) {
;                 const int qp = wq * 32 + qt * 16 + l16;
;                 float sv[8]; float mx = -1e30f;
; #pragma unroll
;                 for (int kt = 0; kt < 2; ++kt)
; #pragma unroll
;                     for (int r = 0; r < 4; ++r) {
;                         const int kp = (kbi - 1) * 128 + si * 32 + kt * 16 + kg * 4 + r;
;                         const int rel = kp - qp; const bool valid = (rel >= -128) && (rel <= 128);
;                         const int idx = min(max(rel + 128, 0), 256);
;                         const float v = valid ? (sa[kt][qt][r] * SC + bL[hl * 260 + idx]) : -1e30f;
;                         sv[kt * 4 + r] = v; mx = fmaxf(mx, v);
;                     }
;     ...
;             for (int dt = 0; dt < 8; ++dt) {
;                 const LAS unsigned char* vr = Vt + (dt * 16 + l16) * 288 + (si * 32 + kg * 4) * 2;
;                 const u32x2 lo = *(const LAS u32x2*)(vr), hi = *(const LAS u32x2*)(vr + 32);
;                 u32x4 vw; vw.x = lo.x; vw.y = lo.y; vw.z = hi.x; vw.w = hi.y;
;                 const bf16x8 vf = __builtin_bit_cast(bf16x8, vw);
;                 o[dt][0] = __builtin_amdgcn_mfma_f32_16x16x32_bf16(vf, pf[0], o[dt][0], 0, 0, 0);
;                 o[dt][1] = __builtin_amdgcn_mfma_f32_16x16x32_bf16(vf, pf[1], o[dt][1], 0, 0, 0);
	v_mfma_f32_16x16x32_bf16 v[96:99], v[236:239], v[132:135], v[96:99]
	v_mov_b32_e32 v222, v3
	v_mfma_f32_16x16x32_bf16 v[68:71], v[236:239], v[136:139], v[68:71]
	v_add_u32_e32 v252, 0xd000, v141
	ds_read2_b64 v[236:239], v252 offset0:8 offset1:12
	s_waitcnt lgkmcnt(3)
	v_mfma_f32_16x16x32_bf16 v[104:107], v[240:243], v[132:135], v[104:107]
	v_mfma_f32_16x16x32_bf16 v[72:75], v[240:243], v[136:139], v[72:75]
	v_add_u32_e32 v252, 0xe000, v141
	ds_read2_b64 v[240:243], v252 offset0:72 offset1:76
	v_add_u32_e32 v141, 0xf000, v141
	s_waitcnt lgkmcnt(3)
	v_mfma_f32_16x16x32_bf16 v[108:111], v[244:247], v[132:135], v[108:111]
	v_mfma_f32_16x16x32_bf16 v[76:79], v[244:247], v[136:139], v[76:79]
	ds_read2_b64 v[244:247], v141 offset0:136 offset1:140
	s_waitcnt lgkmcnt(3)
	v_mfma_f32_16x16x32_bf16 v[112:115], v[248:251], v[132:135], v[112:115]
	v_mfma_f32_16x16x32_bf16 v[80:83], v[248:251], v[136:139], v[80:83]
	ds_read2_b64 v[248:251], v216 offset0:192 offset1:196
	s_waitcnt lgkmcnt(3)
	v_mfma_f32_16x16x32_bf16 v[116:119], v[236:239], v[132:135], v[116:119]
	v_mfma_f32_16x16x32_bf16 v[84:87], v[236:239], v[136:139], v[84:87]
	s_waitcnt lgkmcnt(2)
	v_mfma_f32_16x16x32_bf16 v[120:123], v[240:243], v[132:135], v[120:123]
	v_mfma_f32_16x16x32_bf16 v[88:91], v[240:243], v[136:139], v[88:91]
	s_waitcnt lgkmcnt(1)
	v_mfma_f32_16x16x32_bf16 v[124:127], v[244:247], v[132:135], v[124:127]
	v_mfma_f32_16x16x32_bf16 v[92:95], v[244:247], v[136:139], v[92:95]
	s_waitcnt lgkmcnt(0)
	v_mfma_f32_16x16x32_bf16 v[128:131], v[248:251], v[132:135], v[128:131]
	v_mfma_f32_16x16x32_bf16 v[100:103], v[248:251], v[136:139], v[100:103]
.LBB0_733:
	s_or_b64 exec, exec, s[74:75]
	s_add_i32 s4, s30, -1
	v_cmp_ge_u32_e32 vcc, s4, v192
	v_cmp_le_u32_e64 s[4:5], s4, v195
	s_and_b64 s[4:5], vcc, s[4:5]
	s_and_saveexec_b64 s[74:75], s[4:5]
	s_cbranch_execz .LBB0_767
	v_add_u32_e32 v251, 0x11700, v201
	v_add_u32_e32 v251, v251, v196
	ds_read_b32 v235, v251 offset:512
	ds_read_b32 v236, v251 offset:516
	ds_read_b32 v237, v251 offset:520
	ds_read_b32 v238, v251 offset:524
	ds_read_b32 v239, v251 offset:576
	ds_read_b32 v240, v251 offset:580
	ds_read_b32 v241, v251 offset:584
	ds_read_b32 v242, v251 offset:588
	ds_read_b32 v243, v251 offset:448
	ds_read_b32 v244, v251 offset:452
	ds_read_b32 v245, v251 offset:456
	ds_read_b32 v246, v251 offset:460
	ds_read_b32 v247, v251 offset:512
	ds_read_b32 v248, v251 offset:516
	ds_read_b32 v249, v251 offset:520
	ds_read_b32 v250, v251 offset:524
	ds_read_b128 v[132:135], v211
	ds_read_b128 v[226:229], v211 offset:64
	ds_read_b128 v[140:143], v213 offset:21760
	v_subrev_u32_e32 v1, 51, v199
	v_cmp_gt_u32_e32 vcc, s53, v1
	v_add3_u32 v2, v201, v196, s14
	s_waitcnt lgkmcnt(0)
	v_mfma_f32_16x16x32_bf16 v[136:139], v[132:135], v[4:7], 0
	v_mfma_f32_16x16x32_bf16 v[132:135], v[132:135], v[20:23], 0
	v_mfma_f32_16x16x32_bf16 v[136:139], v[226:229], v[8:11], v[136:139]
	v_mfma_f32_16x16x32_bf16 v[132:135], v[226:229], v[24:27], v[132:135]
	ds_read_b128 v[226:229], v213 offset:21824
	v_mfma_f32_16x16x32_bf16 v[144:147], v[140:143], v[4:7], 0
	v_mfma_f32_16x16x32_bf16 v[140:143], v[140:143], v[20:23], 0
	s_waitcnt lgkmcnt(0)
	v_mfma_f32_16x16x32_bf16 v[144:147], v[226:229], v[8:11], v[144:147]
	v_mfma_f32_16x16x32_bf16 v[140:143], v[226:229], v[24:27], v[140:143]
	ds_read_b128 v[226:229], v211 offset:128
	s_waitcnt lgkmcnt(0)
	v_mfma_f32_16x16x32_bf16 v[136:139], v[226:229], v[12:15], v[136:139]
	v_mfma_f32_16x16x32_bf16 v[132:135], v[226:229], v[28:31], v[132:135]
	ds_read_b128 v[226:229], v213 offset:21888
	s_waitcnt lgkmcnt(0)
	v_mfma_f32_16x16x32_bf16 v[230:233], v[226:229], v[12:15], v[144:147]
	v_mfma_f32_16x16x32_bf16 v[226:229], v[226:229], v[28:31], v[140:143]
	s_nop 2
	ds_read_b128 v[140:143], v211 offset:192
	s_waitcnt lgkmcnt(0)
	v_mfma_f32_16x16x32_bf16 v[144:147], v[140:143], v[16:19], v[136:139]
	s_nop 2
	ds_read_b128 v[136:139], v213 offset:21952
	v_mfma_f32_16x16x32_bf16 v[140:143], v[140:143], v[32:35], v[132:135]
	s_waitcnt lgkmcnt(0)
	v_mfma_f32_16x16x32_bf16 v[132:135], v[136:139], v[16:19], v[230:233]
	v_mfma_f32_16x16x32_bf16 v[136:139], v[136:139], v[32:35], v[226:229]
	s_nop 2
	v_mov_b32_e32 v228, 0xf149f2ca
	v_mov_b32_e32 v229, 0xf149f2ca
	s_waitcnt lgkmcnt(0)
	v_fmac_f32_e32 v235, 0x3e0293ee, v144
	v_cndmask_b32_e32 v229, v229, v235, vcc
	v_subrev_u32_e32 v1, 50, v199
	v_cmp_gt_u32_e64 s[4:5], s53, v1
	v_add3_u32 v225, v201, v196, s54
	v_fmac_f32_e32 v236, 0x3e0293ee, v145
	v_cndmask_b32_e64 v228, v228, v236, s[4:5]
	v_subrev_u32_e32 v1, 49, v199
	v_cmp_gt_u32_e64 s[6:7], s53, v1
	v_mov_b32_e32 v145, 0xf149f2ca
	v_add3_u32 v226, v201, v196, s58
	v_mov_b32_e32 v230, 0xf149f2ca
	v_fmac_f32_e32 v237, 0x3e0293ee, v146
	v_cndmask_b32_e64 v230, v230, v237, s[6:7]
	v_subrev_u32_e32 v1, 48, v199
	v_cmp_gt_u32_e64 s[8:9], s53, v1
	v_add3_u32 v227, v201, v196, s97
	v_fmac_f32_e32 v238, 0x3e0293ee, v147
	v_cndmask_b32_e64 v145, v145, v238, s[8:9]
	v_subrev_u32_e32 v1, 35, v199
	v_cmp_gt_u32_e64 s[10:11], s53, v1
	v_mov_b32_e32 v232, 0xf149f2ca
	v_mov_b32_e32 v231, 0xf149f2ca
	v_fmac_f32_e32 v239, 0x3e0293ee, v132
	v_cndmask_b32_e64 v231, v231, v239, s[10:11]
	v_subrev_u32_e32 v1, 34, v199
	v_cmp_gt_u32_e64 s[10:11], s53, v1
	v_fmac_f32_e32 v240, 0x3e0293ee, v133
	s_nop 0
	v_cndmask_b32_e64 v232, v232, v240, s[10:11]
	v_subrev_u32_e32 v1, 33, v199
	v_cmp_gt_u32_e64 s[10:11], s53, v1
	v_mov_b32_e32 v132, 0xf149f2ca
	v_mov_b32_e32 v133, 0xf149f2ca
	v_fmac_f32_e32 v241, 0x3e0293ee, v134
	v_cndmask_b32_e64 v133, v133, v241, s[10:11]
	v_subrev_u32_e32 v1, 32, v199
	v_cmp_gt_u32_e64 s[10:11], s53, v1
	v_fmac_f32_e32 v242, 0x3e0293ee, v135
	s_nop 0
	v_cndmask_b32_e64 v132, v132, v242, s[10:11]
	v_mov_b32_e32 v144, 0xf149f2ca
	v_and_b32_e32 v134, 64, v182
	v_max3_f32 v1, v229, v144, v228
	v_xor_b32_e32 v3, 16, v182
	v_add_u32_e32 v134, 64, v134
	v_max3_f32 v1, v1, v230, v145
	v_cmp_lt_i32_e64 s[10:11], v3, v134
	v_max3_f32 v1, v1, v231, v232
	v_max3_f32 v1, v1, v133, v132
	v_cndmask_b32_e64 v3, v182, v3, s[10:11]
	v_lshlrev_b32_e32 v146, 2, v3
	v_mov_b32_e32 v253, v1
	v_mov_b32_e32 v135, v1
	s_nop 1
	v_permlane16_swap_b32_e32 v253, v135
	v_max_f32_e32 v135, v135, v253
	v_xor_b32_e32 v3, 32, v182
	v_cmp_lt_i32_e64 s[10:11], v3, v134
	s_waitcnt lgkmcnt(0)
; #define LAS __attribute__((address_space(3)))
; __device__ __forceinline__ unsigned cvt_pk_bf16(float lo, float hi) { unsigned r; asm volatile("v_cvt_pk_bf16_f32 %0, %1, %2" : "=v"(r) : "v"(lo), "v"(hi)); return r; }
; __device__ __forceinline__ void attn_unit(LAS unsigned char* lds, bf16_t* proj, const float* biasG, const float* sink, int s, int qb, int kh, int hp, bf16_t* dummy = nullptr) {
;     ...
;                 mx = fmaxf(mx, __shfl_xor(mx, 16)); mx = fmaxf(mx, __shfl_xor(mx, 32));
;                 const float mnew = fmaxf(m2[qt], mx), alpha = __builtin_amdgcn_exp2f(m2[qt] - mnew); m2[qt] = mnew;
;                 float ps = 0.f; float pv[8];
; #pragma unroll
;                 for (int i = 0; i < 8; ++i) { pv[i] = __builtin_amdgcn_exp2f(sv[i] - mnew); ps += pv[i]; }
;                 lsum[qt] = lsum[qt] * alpha + ps;
; #pragma unroll
;                 for (int dt = 0; dt < 8; ++dt) o[dt][qt] = o[dt][qt] * alpha;
;                 u32x4 pw; pw.x = cvt_pk_bf16(pv[0], pv[1]); pw.y = cvt_pk_bf16(pv[2], pv[3]); pw.z = cvt_pk_bf16(pv[4], pv[5]); pw.w = cvt_pk_bf16(pv[6], pv[7]);
;                 pf[qt] = __builtin_bit_cast(bf16x8, pw);
;             }
; #pragma unroll
;             for (int dt = 0; dt < 8; ++dt) {
;                 const LAS unsigned char* vr = Vt + (dt * 16 + l16) * 288 + (si * 32 + kg * 4) * 2;
;                 const u32x2 lo = *(const LAS u32x2*)(vr), hi = *(const LAS u32x2*)(vr + 32);
	v_max_f32_e32 v134, v135, v135
	v_cndmask_b32_e64 v3, v182, v3, s[10:11]
	v_lshlrev_b32_e32 v3, 2, v3
	v_max_f32_e32 v1, v1, v134
	v_mov_b32_e32 v253, v1
	v_mov_b32_e32 v134, v1
	s_nop 1
	v_permlane32_swap_b32_e32 v253, v134
	v_max_f32_e32 v134, v134, v253
	s_waitcnt lgkmcnt(0)
	v_max3_f32 v1, v224, v1, v134
	v_sub_f32_e32 v134, v229, v1
	v_exp_f32_e32 v147, v134
	v_sub_f32_e32 v134, v228, v1
	v_exp_f32_e32 v228, v134
	v_sub_f32_e32 v134, v230, v1
	v_exp_f32_e32 v229, v134
	v_sub_f32_e32 v134, v145, v1
	v_exp_f32_e32 v230, v134
	v_sub_f32_e32 v134, v231, v1
	v_exp_f32_e32 v231, v134
	v_sub_f32_e32 v134, v232, v1
	v_sub_f32_e32 v133, v133, v1
	v_sub_f32_e32 v132, v132, v1
	v_exp_f32_e32 v232, v134
	v_exp_f32_e32 v233, v133
	v_exp_f32_e32 v234, v132
	v_add_u32_e32 v145, 0xffffffbd, v199
	v_cmp_gt_u32_e64 s[10:11], s53, v145
	v_mov_b32_e32 v145, 0xf149f2ca
	v_cvt_pk_bf16_f32 v132, v147, v228
	v_cvt_pk_bf16_f32 v133, v229, v230
	v_cvt_pk_bf16_f32 v134, v231, v232
	v_cvt_pk_bf16_f32 v135, v233, v234
	v_fmac_f32_e32 v243, 0x3e0293ee, v140
	v_cndmask_b32_e64 v145, v145, v243, s[10:11]
	v_add_u32_e32 v140, 0xffffffbe, v199
	v_cmp_gt_u32_e64 s[10:11], s53, v140
	v_fmac_f32_e32 v244, 0x3e0293ee, v141
	s_nop 0
	v_cndmask_b32_e64 v144, v144, v244, s[10:11]
	v_add_u32_e32 v140, 0xffffffbf, v199
	v_cmp_gt_u32_e64 s[10:11], s53, v140
	v_mov_b32_e32 v140, 0xf149f2ca
	v_mov_b32_e32 v141, 0xf149f2ca
	v_fmac_f32_e32 v245, 0x3e0293ee, v142
	v_cndmask_b32_e64 v141, v141, v245, s[10:11]
	v_subrev_u32_e32 v142, 64, v199
	v_cmp_gt_u32_e64 s[10:11], s53, v142
	v_fmac_f32_e32 v246, 0x3e0293ee, v143
	s_nop 0
	v_cndmask_b32_e64 v140, v140, v246, s[10:11]
	v_mov_b32_e32 v142, 0xf149f2ca
	v_mov_b32_e32 v143, 0xf149f2ca
	v_fmac_f32_e32 v247, 0x3e0293ee, v136
	v_cndmask_b32_e32 v143, v143, v247, vcc
	v_fmac_f32_e32 v248, 0x3e0293ee, v137
	v_cndmask_b32_e64 v142, v142, v248, s[4:5]
	v_mov_b32_e32 v136, 0xf149f2ca
	v_mov_b32_e32 v137, 0xf149f2ca
	v_fmac_f32_e32 v249, 0x3e0293ee, v138
	v_cndmask_b32_e64 v137, v137, v249, s[6:7]
	v_fmac_f32_e32 v250, 0x3e0293ee, v139
	v_cndmask_b32_e64 v136, v136, v250, s[8:9]
	v_max3_f32 v2, v145, s89, v144
	v_max3_f32 v2, v2, v141, v140
	v_max3_f32 v139, v2, v143, v142
	v_add_f32_e32 v2, 0, v147
	v_add_f32_e32 v2, v228, v2
	v_add_f32_e32 v2, v229, v2
	v_sub_f32_e32 v138, v224, v1
	v_add_f32_e32 v2, v230, v2
	v_add_f32_e32 v2, v231, v2
	v_exp_f32_e32 v138, v138
	v_add_f32_e32 v2, v232, v2
	v_add_f32_e32 v2, v233, v2
	v_add_f32_e32 v2, v234, v2
	v_fmac_f32_e32 v2, v223, v138
	v_pk_mul_f32 v[98:99], v[98:99], v[138:139] op_sel_hi:[1,0]
	v_pk_mul_f32 v[96:97], v[96:97], v[138:139] op_sel_hi:[1,0]
	v_pk_mul_f32 v[106:107], v[106:107], v[138:139] op_sel_hi:[1,0]
	v_pk_mul_f32 v[104:105], v[104:105], v[138:139] op_sel_hi:[1,0]
	v_pk_mul_f32 v[110:111], v[110:111], v[138:139] op_sel_hi:[1,0]
	v_pk_mul_f32 v[108:109], v[108:109], v[138:139] op_sel_hi:[1,0]
	v_pk_mul_f32 v[114:115], v[114:115], v[138:139] op_sel_hi:[1,0]
	v_pk_mul_f32 v[112:113], v[112:113], v[138:139] op_sel_hi:[1,0]
	v_pk_mul_f32 v[118:119], v[118:119], v[138:139] op_sel_hi:[1,0]
	v_pk_mul_f32 v[116:117], v[116:117], v[138:139] op_sel_hi:[1,0]
	v_pk_mul_f32 v[122:123], v[122:123], v[138:139] op_sel_hi:[1,0]
	v_pk_mul_f32 v[120:121], v[120:121], v[138:139] op_sel_hi:[1,0]
	v_pk_mul_f32 v[126:127], v[126:127], v[138:139] op_sel_hi:[1,0]
	v_pk_mul_f32 v[124:125], v[124:125], v[138:139] op_sel_hi:[1,0]
	v_pk_mul_f32 v[130:131], v[130:131], v[138:139] op_sel_hi:[1,0]
	v_pk_mul_f32 v[128:129], v[128:129], v[138:139] op_sel_hi:[1,0]
	v_max3_f32 v138, v139, v137, v136
	v_mov_b32_e32 v253, v138
	v_mov_b32_e32 v139, v138
	s_nop 1
	v_permlane16_swap_b32_e32 v253, v139
	v_max_f32_e32 v139, v139, v253
	v_mov_b32_e32 v223, v2
	v_mov_b32_e32 v224, v1
	s_waitcnt lgkmcnt(0)
	v_max_f32_e32 v139, v139, v139
	v_max_f32_e32 v138, v138, v139
	v_mov_b32_e32 v253, v138
	v_mov_b32_e32 v3, v138
	s_nop 1
	v_permlane32_swap_b32_e32 v253, v3
	v_max_f32_e32 v3, v3, v253
	s_waitcnt lgkmcnt(0)
	v_max3_f32 v3, v222, v138, v3
	v_sub_f32_e32 v139, v145, v3
	v_exp_f32_e32 v139, v139
	v_sub_f32_e32 v144, v144, v3
	v_exp_f32_e32 v144, v144
	v_sub_f32_e32 v141, v141, v3
	v_exp_f32_e32 v141, v141
	v_sub_f32_e32 v140, v140, v3
	v_exp_f32_e32 v146, v140
	v_add_f32_e32 v145, 0, v139
	v_sub_f32_e32 v143, v143, v3
	v_add_f32_e32 v145, v144, v145
	v_exp_f32_e32 v143, v143
	v_sub_f32_e32 v142, v142, v3
	v_add_f32_e32 v145, v141, v145
	v_exp_f32_e32 v142, v142
	v_sub_f32_e32 v137, v137, v3
	v_add_f32_e32 v140, v146, v145
	v_exp_f32_e32 v145, v137
	v_sub_f32_e32 v136, v136, v3
	v_sub_f32_e32 v138, v222, v3
	v_exp_f32_e32 v147, v136
	v_add_f32_e32 v140, v143, v140
	v_exp_f32_e32 v136, v138
	v_add_f32_e32 v140, v142, v140
	v_add_f32_e32 v137, v145, v140
	v_add_f32_e32 v140, v147, v137
	v_fmac_f32_e32 v140, v221, v136
	v_pk_mul_f32 v[70:71], v[70:71], v[136:137] op_sel_hi:[1,0]
	v_pk_mul_f32 v[68:69], v[68:69], v[136:137] op_sel_hi:[1,0]
	v_pk_mul_f32 v[74:75], v[74:75], v[136:137] op_sel_hi:[1,0]
	v_pk_mul_f32 v[72:73], v[72:73], v[136:137] op_sel_hi:[1,0]
	v_pk_mul_f32 v[78:79], v[78:79], v[136:137] op_sel_hi:[1,0]
	v_pk_mul_f32 v[76:77], v[76:77], v[136:137] op_sel_hi:[1,0]
	v_pk_mul_f32 v[82:83], v[82:83], v[136:137] op_sel_hi:[1,0]
	v_pk_mul_f32 v[80:81], v[80:81], v[136:137] op_sel_hi:[1,0]
	v_pk_mul_f32 v[86:87], v[86:87], v[136:137] op_sel_hi:[1,0]
	v_pk_mul_f32 v[84:85], v[84:85], v[136:137] op_sel_hi:[1,0]
	v_pk_mul_f32 v[90:91], v[90:91], v[136:137] op_sel_hi:[1,0]
	v_pk_mul_f32 v[88:89], v[88:89], v[136:137] op_sel_hi:[1,0]
	v_pk_mul_f32 v[94:95], v[94:95], v[136:137] op_sel_hi:[1,0]
	v_pk_mul_f32 v[92:93], v[92:93], v[136:137] op_sel_hi:[1,0]
	v_pk_mul_f32 v[102:103], v[102:103], v[136:137] op_sel_hi:[1,0]
	v_pk_mul_f32 v[100:101], v[100:101], v[136:137] op_sel_hi:[1,0]
	v_cvt_pk_bf16_f32 v136, v139, v144
	v_cvt_pk_bf16_f32 v137, v141, v146
	v_add_u32_e32 v141, v197, v198
	v_cvt_pk_bf16_f32 v138, v143, v142
	v_add_u32_e32 v142, 0x8800, v141
	v_cvt_pk_bf16_f32 v139, v145, v147
	ds_read2_b64 v[236:239], v142 offset0:16 offset1:20
	v_mov_b32_e32 v221, v140
	v_add_u32_e32 v252, 0x9800, v141
	ds_read2_b64 v[240:243], v252 offset0:80 offset1:84
	v_add_u32_e32 v252, 0xa800, v141
	ds_read2_b64 v[244:247], v252 offset0:144 offset1:148
	v_add_u32_e32 v252, 0xb800, v141
	ds_read2_b64 v[248:251], v252 offset0:208 offset1:212
	s_waitcnt lgkmcnt(3)
; #define LAS __attribute__((address_space(3)))
; __device__ __forceinline__ void attn_unit(LAS unsigned char* lds, bf16_t* proj, const float* biasG, const float* sink, int s, int qb, int kh, int hp, bf16_t* dummy = nullptr) {
;     ...
;             for (int dt = 0; dt < 8; ++dt) {
;                 const LAS unsigned char* vr = Vt + (dt * 16 + l16) * 288 + (si * 32 + kg * 4) * 2;
;                 const u32x2 lo = *(const LAS u32x2*)(vr), hi = *(const LAS u32x2*)(vr + 32);
;                 u32x4 vw; vw.x = lo.x; vw.y = lo.y; vw.z = hi.x; vw.w = hi.y;
;                 const bf16x8 vf = __builtin_bit_cast(bf16x8, vw);
;                 o[dt][0] = __builtin_amdgcn_mfma_f32_16x16x32_bf16(vf, pf[0], o[dt][0], 0, 0, 0);
;                 o[dt][1] = __builtin_amdgcn_mfma_f32_16x16x32_bf16(vf, pf[1], o[dt][1], 0, 0, 0);
	v_mfma_f32_16x16x32_bf16 v[96:99], v[236:239], v[132:135], v[96:99]
	v_mov_b32_e32 v222, v3
	v_mfma_f32_16x16x32_bf16 v[68:71], v[236:239], v[136:139], v[68:71]
	ds_read2_b64 v[236:239], v217 offset0:16 offset1:20
	s_waitcnt lgkmcnt(3)
	v_mfma_f32_16x16x32_bf16 v[104:107], v[240:243], v[132:135], v[104:107]
	v_mfma_f32_16x16x32_bf16 v[72:75], v[240:243], v[136:139], v[72:75]
	v_add_u32_e32 v252, 0xe000, v141
	ds_read2_b64 v[240:243], v252 offset0:80 offset1:84
	v_add_u32_e32 v141, 0xf000, v141
	s_waitcnt lgkmcnt(3)
	v_mfma_f32_16x16x32_bf16 v[108:111], v[244:247], v[132:135], v[108:111]
	v_mfma_f32_16x16x32_bf16 v[76:79], v[244:247], v[136:139], v[76:79]
	ds_read2_b64 v[244:247], v141 offset0:144 offset1:148
	s_waitcnt lgkmcnt(3)
	v_mfma_f32_16x16x32_bf16 v[112:115], v[248:251], v[132:135], v[112:115]
	v_mfma_f32_16x16x32_bf16 v[80:83], v[248:251], v[136:139], v[80:83]
	ds_read2_b64 v[248:251], v218 offset0:192 offset1:196
	s_waitcnt lgkmcnt(3)
	v_mfma_f32_16x16x32_bf16 v[116:119], v[236:239], v[132:135], v[116:119]
	v_mfma_f32_16x16x32_bf16 v[84:87], v[236:239], v[136:139], v[84:87]
	s_waitcnt lgkmcnt(2)
	v_mfma_f32_16x16x32_bf16 v[120:123], v[240:243], v[132:135], v[120:123]
	v_mfma_f32_16x16x32_bf16 v[88:91], v[240:243], v[136:139], v[88:91]
	s_waitcnt lgkmcnt(1)
	v_mfma_f32_16x16x32_bf16 v[124:127], v[244:247], v[132:135], v[124:127]
	v_mfma_f32_16x16x32_bf16 v[92:95], v[244:247], v[136:139], v[92:95]
	s_waitcnt lgkmcnt(0)
	v_mfma_f32_16x16x32_bf16 v[128:131], v[248:251], v[132:135], v[128:131]
	v_mfma_f32_16x16x32_bf16 v[100:103], v[248:251], v[136:139], v[100:103]
; #define LAS __attribute__((address_space(3)))
; __device__ __forceinline__ void attn_unit(LAS unsigned char* lds, bf16_t* proj, const float* biasG, const float* sink, int s, int qb, int kh, int hp, bf16_t* dummy = nullptr) {
;     ...
;         for (int si = 0; si < 4; ++si) {
;             const int st = kbi * 4 + si;
;             if (st < wq || st > wq + 8) continue;
;             f32x4 sa[2][2];
; #pragma unroll
;             for (int kt = 0; kt < 2; ++kt) { sa[kt][0] = (f32x4){0.f, 0.f, 0.f, 0.f}; sa[kt][1] = (f32x4){0.f, 0.f, 0.f, 0.f}; }
; #pragma unroll
;             for (int ks = 0; ks < 4; ++ks)
; #pragma unroll
;                 for (int kt = 0; kt < 2; ++kt) {
;                     const bf16x8 kf = *(const LAS bf16x8*)(Ks + (si * 32 + kt * 16 + l16) * 272 + ks * 64 + kg * 16);
;                     sa[kt][0] = __builtin_amdgcn_mfma_f32_16x16x32_bf16(kf, qf[0][ks], sa[kt][0], 0, 0, 0);
;                     sa[kt][1] = __builtin_amdgcn_mfma_f32_16x16x32_bf16(kf, qf[1][ks], sa[kt][1], 0, 0, 0);
;                 }
;             bf16x8 pf[2];
; #pragma unroll
;             for (int qt = 0; qt < 2; ++qt) {
;                 const int qp = wq * 32 + qt * 16 + l16;
;                 float sv[8]; float mx = -1e30f;
; #pragma unroll
;                 for (int kt = 0; kt < 2; ++kt)
; #pragma unroll
;                     for (int r = 0; r < 4; ++r) {
;                         const int kp = (kbi - 1) * 128 + si * 32 + kt * 16 + kg * 4 + r;
;                         const int rel = kp - qp; const bool valid = (rel >= -128) && (rel <= 128);
;                         const int idx = min(max(rel + 128, 0), 256);
;                         const float v = valid ? (sa[kt][qt][r] * SC + bL[hl * 260 + idx]) : -1e30f;
;                         sv[kt * 4 + r] = v; mx = fmaxf(mx, v);
;                     }
;                 mx = fmaxf(mx, __shfl_xor(mx, 16)); mx = fmaxf(mx, __shfl_xor(mx, 32));
;                 const float mnew = fmaxf(m2[qt], mx), alpha = __builtin_amdgcn_exp2f(m2[qt] - mnew); m2[qt] = mnew;
;                 float ps = 0.f; float pv[8];
; #pragma unroll
;                 for (int i = 0; i < 8; ++i) { pv[i] = __builtin_amdgcn_exp2f(sv[i] - mnew); ps += pv[i]; }
.LBB0_767:
	s_or_b64 exec, exec, s[74:75]
	v_cmp_le_u32_e32 vcc, s30, v195
	s_and_saveexec_b64 s[74:75], vcc
	s_cbranch_execz .LBB0_662
	v_add_u32_e32 v251, 0x11700, v201
	v_add_u32_e32 v251, v251, v196
	ds_read_b32 v235, v251 offset:640
	ds_read_b32 v236, v251 offset:644
	ds_read_b32 v237, v251 offset:648
	ds_read_b32 v238, v251 offset:652
	ds_read_b32 v239, v251 offset:704
	ds_read_b32 v240, v251 offset:708
	ds_read_b32 v241, v251 offset:712
	ds_read_b32 v242, v251 offset:716
	ds_read_b32 v243, v251 offset:576
	ds_read_b32 v244, v251 offset:580
	ds_read_b32 v245, v251 offset:584
	ds_read_b32 v246, v251 offset:588
	ds_read_b32 v247, v251 offset:640
	ds_read_b32 v248, v251 offset:644
	ds_read_b32 v249, v251 offset:648
	ds_read_b32 v250, v251 offset:652
	ds_read_b128 v[132:135], v212
	ds_read_b128 v[226:229], v212 offset:64
	ds_read_b128 v[140:143], v213 offset:30464
	v_subrev_u32_e32 v1, 19, v199
	v_cmp_gt_u32_e32 vcc, s53, v1
	v_add3_u32 v2, v201, v196, s49
	s_waitcnt lgkmcnt(0)
	v_mfma_f32_16x16x32_bf16 v[136:139], v[132:135], v[4:7], 0
	v_mfma_f32_16x16x32_bf16 v[132:135], v[132:135], v[20:23], 0
	v_mfma_f32_16x16x32_bf16 v[136:139], v[226:229], v[8:11], v[136:139]
	v_mfma_f32_16x16x32_bf16 v[132:135], v[226:229], v[24:27], v[132:135]
	ds_read_b128 v[226:229], v213 offset:30528
	v_mfma_f32_16x16x32_bf16 v[144:147], v[140:143], v[4:7], 0
	v_mfma_f32_16x16x32_bf16 v[140:143], v[140:143], v[20:23], 0
	s_waitcnt lgkmcnt(0)
	v_mfma_f32_16x16x32_bf16 v[144:147], v[226:229], v[8:11], v[144:147]
	v_mfma_f32_16x16x32_bf16 v[140:143], v[226:229], v[24:27], v[140:143]
	ds_read_b128 v[226:229], v212 offset:128
	s_waitcnt lgkmcnt(0)
	v_mfma_f32_16x16x32_bf16 v[136:139], v[226:229], v[12:15], v[136:139]
	v_mfma_f32_16x16x32_bf16 v[132:135], v[226:229], v[28:31], v[132:135]
	ds_read_b128 v[226:229], v213 offset:30592
	s_waitcnt lgkmcnt(0)
	v_mfma_f32_16x16x32_bf16 v[230:233], v[226:229], v[12:15], v[144:147]
	v_mfma_f32_16x16x32_bf16 v[226:229], v[226:229], v[28:31], v[140:143]
	s_nop 2
	ds_read_b128 v[140:143], v212 offset:192
	s_waitcnt lgkmcnt(0)
	v_mfma_f32_16x16x32_bf16 v[144:147], v[140:143], v[16:19], v[136:139]
	s_nop 2
	ds_read_b128 v[136:139], v213 offset:30656
	v_mfma_f32_16x16x32_bf16 v[140:143], v[140:143], v[32:35], v[132:135]
	s_waitcnt lgkmcnt(0)
	v_mfma_f32_16x16x32_bf16 v[132:135], v[136:139], v[16:19], v[230:233]
	v_mfma_f32_16x16x32_bf16 v[136:139], v[136:139], v[32:35], v[226:229]
	s_nop 2
	v_mov_b32_e32 v228, 0xf149f2ca
	v_mov_b32_e32 v229, 0xf149f2ca
	s_waitcnt lgkmcnt(0)
	v_fmac_f32_e32 v235, 0x3e0293ee, v144
	v_cndmask_b32_e32 v229, v229, v235, vcc
	v_subrev_u32_e32 v1, 18, v199
	v_cmp_gt_u32_e64 s[4:5], s53, v1
	v_add3_u32 v225, v201, v196, s0
	v_fmac_f32_e32 v236, 0x3e0293ee, v145
	v_cndmask_b32_e64 v228, v228, v236, s[4:5]
	v_subrev_u32_e32 v1, 17, v199
	v_cmp_gt_u32_e64 s[6:7], s53, v1
	v_mov_b32_e32 v145, 0xf149f2ca
	v_add3_u32 v226, v201, v196, s1
	v_mov_b32_e32 v230, 0xf149f2ca
	v_fmac_f32_e32 v237, 0x3e0293ee, v146
	v_cndmask_b32_e64 v230, v230, v237, s[6:7]
	v_add_u32_e32 v1, -16, v199
	v_cmp_gt_u32_e64 s[8:9], s53, v1
	v_add3_u32 v227, v201, v196, s15
	v_fmac_f32_e32 v238, 0x3e0293ee, v147
	v_cndmask_b32_e64 v145, v145, v238, s[8:9]
	v_add_u32_e32 v1, -3, v199
	v_cmp_gt_u32_e64 s[10:11], s53, v1
	v_mov_b32_e32 v232, 0xf149f2ca
	v_mov_b32_e32 v231, 0xf149f2ca
	v_fmac_f32_e32 v239, 0x3e0293ee, v132
	v_cndmask_b32_e64 v231, v231, v239, s[10:11]
	v_add_u32_e32 v1, -2, v199
	v_cmp_gt_u32_e64 s[10:11], s53, v1
	v_fmac_f32_e32 v240, 0x3e0293ee, v133
	s_nop 0
	v_cndmask_b32_e64 v232, v232, v240, s[10:11]
	v_add_u32_e32 v1, -1, v199
	v_cmp_gt_u32_e64 s[10:11], s53, v1
	v_mov_b32_e32 v132, 0xf149f2ca
	v_mov_b32_e32 v133, 0xf149f2ca
	v_fmac_f32_e32 v241, 0x3e0293ee, v134
	v_cndmask_b32_e64 v133, v133, v241, s[10:11]
	v_cmp_gt_u32_e64 s[10:11], s53, v199
	v_fmac_f32_e32 v242, 0x3e0293ee, v135
	s_nop 0
	v_cndmask_b32_e64 v132, v132, v242, s[10:11]
	v_mov_b32_e32 v144, 0xf149f2ca
	v_and_b32_e32 v134, 64, v182
	v_max3_f32 v1, v229, v144, v228
	v_xor_b32_e32 v3, 16, v182
	v_add_u32_e32 v134, 64, v134
	v_max3_f32 v1, v1, v230, v145
	v_cmp_lt_i32_e64 s[10:11], v3, v134
	v_max3_f32 v1, v1, v231, v232
	v_max3_f32 v1, v1, v133, v132
	v_cndmask_b32_e64 v3, v182, v3, s[10:11]
	v_lshlrev_b32_e32 v146, 2, v3
	v_mov_b32_e32 v253, v1
	v_mov_b32_e32 v135, v1
	s_nop 1
	v_permlane16_swap_b32_e32 v253, v135
	v_max_f32_e32 v135, v135, v253
	v_xor_b32_e32 v3, 32, v182
	v_cmp_lt_i32_e64 s[10:11], v3, v134
	s_waitcnt lgkmcnt(0)
	v_max_f32_e32 v134, v135, v135
	v_cndmask_b32_e64 v3, v182, v3, s[10:11]
	v_lshlrev_b32_e32 v3, 2, v3
	v_max_f32_e32 v1, v1, v134
	v_mov_b32_e32 v253, v1
	v_mov_b32_e32 v134, v1
	s_nop 1
	v_permlane32_swap_b32_e32 v253, v134
	v_max_f32_e32 v134, v134, v253
	s_waitcnt lgkmcnt(0)
	v_max3_f32 v1, v224, v1, v134
	v_sub_f32_e32 v134, v229, v1
	v_exp_f32_e32 v147, v134
	v_sub_f32_e32 v134, v228, v1
	v_exp_f32_e32 v228, v134
	v_sub_f32_e32 v134, v230, v1
	v_exp_f32_e32 v229, v134
	v_sub_f32_e32 v134, v145, v1
	v_exp_f32_e32 v230, v134
	v_sub_f32_e32 v134, v231, v1
	v_exp_f32_e32 v231, v134
	v_sub_f32_e32 v134, v232, v1
	v_sub_f32_e32 v133, v133, v1
	v_sub_f32_e32 v132, v132, v1
	v_exp_f32_e32 v232, v134
	v_exp_f32_e32 v233, v133
	v_exp_f32_e32 v234, v132
	v_subrev_u32_e32 v145, 35, v199
	v_cmp_gt_u32_e64 s[10:11], s53, v145
	v_mov_b32_e32 v145, 0xf149f2ca
	v_cvt_pk_bf16_f32 v132, v147, v228
	v_cvt_pk_bf16_f32 v133, v229, v230
	v_cvt_pk_bf16_f32 v134, v231, v232
	v_cvt_pk_bf16_f32 v135, v233, v234
	v_fmac_f32_e32 v243, 0x3e0293ee, v140
	v_cndmask_b32_e64 v145, v145, v243, s[10:11]
	v_subrev_u32_e32 v140, 34, v199
	v_cmp_gt_u32_e64 s[10:11], s53, v140
	v_fmac_f32_e32 v244, 0x3e0293ee, v141
	s_nop 0
	v_cndmask_b32_e64 v144, v144, v244, s[10:11]
	v_subrev_u32_e32 v140, 33, v199
	v_cmp_gt_u32_e64 s[10:11], s53, v140
	v_mov_b32_e32 v140, 0xf149f2ca
	v_mov_b32_e32 v141, 0xf149f2ca
	v_fmac_f32_e32 v245, 0x3e0293ee, v142
	v_cndmask_b32_e64 v141, v141, v245, s[10:11]
	v_subrev_u32_e32 v142, 32, v199
	v_cmp_gt_u32_e64 s[10:11], s53, v142
	v_fmac_f32_e32 v246, 0x3e0293ee, v143
	s_nop 0
	v_cndmask_b32_e64 v140, v140, v246, s[10:11]
	v_mov_b32_e32 v142, 0xf149f2ca
	v_mov_b32_e32 v143, 0xf149f2ca
	v_fmac_f32_e32 v247, 0x3e0293ee, v136
	v_cndmask_b32_e32 v143, v143, v247, vcc
	v_fmac_f32_e32 v248, 0x3e0293ee, v137
	v_cndmask_b32_e64 v142, v142, v248, s[4:5]
	v_mov_b32_e32 v136, 0xf149f2ca
	v_mov_b32_e32 v137, 0xf149f2ca
	v_fmac_f32_e32 v249, 0x3e0293ee, v138
	v_cndmask_b32_e64 v137, v137, v249, s[6:7]
	s_and_saveexec_b64 s[4:5], s[8:9]
	s_cbranch_execz .LBB0_661
	v_mov_b32_e32 v136, v250
	v_fmac_f32_e32 v136, 0x3e0293ee, v139
	s_branch .LBB0_661
